# GEMM K-loops: LDS-DMA loads take SGPR base + 32-bit VGPR offset (no per-load 64-bit VALU address add); next-K-tile bases kept in 2 scratch SGPR pairs
# speedup vs baseline: 1.0364x; 1.0094x over previous
; #define PG8_STAGE(bufoff, gbase, voff) do { _Pragma("unroll") for (int _i = 0; _i < 2; ++_i) \
;         __builtin_amdgcn_global_load_lds((const unsigned*)((const char*)(gbase) + (voff)[_i]), (PG8_LAS unsigned*)(lds + (bufoff) + ldsw + _i * 8192), 16, 0, 0); } while (0)
; #define PG8_LDA(dst, b, h) do { _Pragma("unroll") for (int m = 0; m < 4; ++m) _Pragma("unroll") for (int k = 0; k < 2; ++k) dst[m][k] = *(const PG8_LAS bf16x8*)(lds + PG8_SA(b, h) + aoff + m * 2048 + k * 1024); } while (0)
; #define PG8_LDB(dst, b, h) do { _Pragma("unroll") for (int n = 0; n < 2; ++n) _Pragma("unroll") for (int k = 0; k < 2; ++k) dst[n][k] = *(const PG8_LAS bf16x8*)(lds + PG8_SB(b, h) + boff + n * 2048 + k * 1024); } while (0)
; #define PG8_MMA(ai, bj, At, Bt) do { __builtin_amdgcn_s_setprio(1); _Pragma("unroll") for (int m = 0; m < 4; ++m) _Pragma("unroll") for (int n = 0; n < 2; ++n) _Pragma("unroll") for (int k = 0; k < 2; ++k) \
;         acc[ai][bj][m][n] = __builtin_amdgcn_mfma_f32_16x16x32_bf16(Bt[n][k], At[m][k], acc[ai][bj][m][n], 0, 0, 0); __builtin_amdgcn_s_setprio(0); } while (0)
; #define PG8_WAIT_V(n) asm volatile("s_waitcnt vmcnt(" #n ")" ::: "memory")
; #define PG8_WAIT_L(n) asm volatile("s_waitcnt lgkmcnt(" #n ")" ::: "memory")
; #define PG8_BAR __builtin_amdgcn_s_barrier()
; #define PG8_SCHED __builtin_amdgcn_sched_barrier(0)
; template <class Epi, class Sched, bool ALIGN_EPI = false, bool SP2 = false>
; __device__ __forceinline__ void gemm_phase(PG8_LAS unsigned char* lds, const Gemm g, const Sched& S, const Epi& E) {
;     ...
;             PG8_LDB(B0, 0, 0); PG8_LDB(B1, 0, 1); PG8_SCHED; PG8_LDA(At, 0, 0); PG8_STAGE(PG8_SA(1, 1), a1 + hstep, voffA);
;             PG8_WAIT_V(8); PG8_WAIT_L(0); PG8_BAR; PG8_MMA(0, 0, At, B0); PG8_MMA(0, 1, At, B1); PG8_BAR; PG8_SCHED;
;             PG8_LDA(At, 0, 1); PG8_STAGE(PG8_SB(0, 0), b2, voffB); PG8_STAGE(PG8_SB(0, 1), b2 + hstep, voffB); PG8_STAGE(PG8_SA(0, 0), a2, voffA);
;             PG8_WAIT_V(8); PG8_WAIT_L(0); PG8_BAR; PG8_MMA(1, 0, At, B0); PG8_MMA(1, 1, At, B1); PG8_BAR; PG8_SCHED;
;             PG8_LDB(B0, 1, 0); PG8_LDB(B1, 1, 1); PG8_SCHED; PG8_LDA(At, 1, 0); PG8_STAGE(PG8_SA(0, 1), a2 + hstep, voffA);
;             PG8_WAIT_V(8); PG8_WAIT_L(0); PG8_BAR; PG8_MMA(0, 0, At, B0); PG8_MMA(0, 1, At, B1); PG8_BAR; PG8_SCHED;
.LBB0_104:
	ds_read_b128 v[128:131], v173
	ds_read_b128 v[132:135], v173 offset:1024
	ds_read_b128 v[156:159], v173 offset:2048
	ds_read_b128 v[180:183], v173 offset:3072
	ds_read_b128 v[184:187], v174
	ds_read_b128 v[188:191], v174 offset:1024
	ds_read_b128 v[192:195], v174 offset:2048
	ds_read_b128 v[200:203], v174 offset:3072
	s_add_u32 s2, s30, 0xfff80080
	s_addc_u32 s3, s31, -1
	s_cmp_eq_u32 s73, 28
	s_cselect_b32 s5, s7, s3
	s_cselect_b32 s4, s23, s2
	s_cselect_b32 s3, s21, s72
	s_cselect_b32 s2, s70, s71
	s_add_i32 m0, s29, 0xc000
	ds_read_b128 v[204:207], v175
	ds_read_b128 v[208:211], v175 offset:1024
	ds_read_b128 v[212:215], v175 offset:2048
	ds_read_b128 v[216:219], v175 offset:3072
	ds_read_b128 v[220:223], v175 offset:4096
	ds_read_b128 v[224:227], v175 offset:5120
	ds_read_b128 v[228:231], v175 offset:6144
	ds_read_b128 v[232:235], v175 offset:7168
	global_load_lds_dwordx4 v146, s[30:31]
	s_add_i32 m0, s29, 0xe000
	s_nop 0
	global_load_lds_dwordx4 v148, s[30:31]
	s_waitcnt vmcnt(8)
	s_waitcnt lgkmcnt(0)
	s_barrier
	s_setprio 1
	s_waitcnt lgkmcnt(0)
	v_mfma_f32_16x16x32_bf16 v[124:127], v[128:131], v[204:207], v[124:127]
	v_mfma_f32_16x16x32_bf16 v[120:123], v[156:159], v[204:207], v[120:123]
	v_mfma_f32_16x16x32_bf16 v[116:119], v[128:131], v[212:215], v[116:119]
	v_mfma_f32_16x16x32_bf16 v[112:115], v[156:159], v[212:215], v[112:115]
	v_mfma_f32_16x16x32_bf16 v[100:103], v[128:131], v[220:223], v[100:103]
	v_mfma_f32_16x16x32_bf16 v[96:99], v[156:159], v[220:223], v[96:99]
	v_mfma_f32_16x16x32_bf16 v[84:87], v[128:131], v[228:231], v[84:87]
	v_mfma_f32_16x16x32_bf16 v[80:83], v[156:159], v[228:231], v[80:83]
	v_mfma_f32_16x16x32_bf16 v[124:127], v[132:135], v[208:211], v[124:127]
	v_mfma_f32_16x16x32_bf16 v[120:123], v[180:183], v[208:211], v[120:123]
	v_mfma_f32_16x16x32_bf16 v[116:119], v[132:135], v[216:219], v[116:119]
	v_mfma_f32_16x16x32_bf16 v[112:115], v[180:183], v[216:219], v[112:115]
	v_mfma_f32_16x16x32_bf16 v[100:103], v[132:135], v[224:227], v[100:103]
	v_mfma_f32_16x16x32_bf16 v[96:99], v[180:183], v[224:227], v[96:99]
	v_mfma_f32_16x16x32_bf16 v[84:87], v[132:135], v[232:235], v[84:87]
	v_mfma_f32_16x16x32_bf16 v[80:83], v[180:183], v[232:235], v[80:83]
	s_setprio 0
	s_setprio 1
	v_mfma_f32_16x16x32_bf16 v[108:111], v[184:187], v[204:207], v[108:111]
	v_mfma_f32_16x16x32_bf16 v[104:107], v[192:195], v[204:207], v[104:107]
	v_mfma_f32_16x16x32_bf16 v[92:95], v[184:187], v[212:215], v[92:95]
	v_mfma_f32_16x16x32_bf16 v[88:91], v[192:195], v[212:215], v[88:91]
	v_mfma_f32_16x16x32_bf16 v[76:79], v[184:187], v[220:223], v[76:79]
	v_mfma_f32_16x16x32_bf16 v[72:75], v[192:195], v[220:223], v[72:75]
	v_mfma_f32_16x16x32_bf16 v[68:71], v[184:187], v[228:231], v[68:71]
	v_mfma_f32_16x16x32_bf16 v[64:67], v[192:195], v[228:231], v[64:67]
	v_mfma_f32_16x16x32_bf16 v[108:111], v[188:191], v[208:211], v[108:111]
	v_mfma_f32_16x16x32_bf16 v[104:107], v[200:203], v[208:211], v[104:107]
	v_mfma_f32_16x16x32_bf16 v[92:95], v[188:191], v[216:219], v[92:95]
	v_mfma_f32_16x16x32_bf16 v[88:91], v[200:203], v[216:219], v[88:91]
	v_mfma_f32_16x16x32_bf16 v[76:79], v[188:191], v[224:227], v[76:79]
	v_mfma_f32_16x16x32_bf16 v[72:75], v[200:203], v[224:227], v[72:75]
	v_mfma_f32_16x16x32_bf16 v[68:71], v[188:191], v[232:235], v[68:71]
	v_mfma_f32_16x16x32_bf16 v[64:67], v[200:203], v[232:235], v[64:67]
	s_setprio 0
	s_barrier
	s_add_u32 s98, s2, s14
	s_addc_u32 s99, s3, s15
	s_add_u32 s100, s4, s14
	s_addc_u32 s101, s5, s15
	s_add_i32 s74, s57, s33
	s_mov_b32 m0, s74
	ds_read_b128 v[204:207], v175 offset:16384
	ds_read_b128 v[208:211], v175 offset:17408
	ds_read_b128 v[212:215], v175 offset:18432
	ds_read_b128 v[216:219], v175 offset:19456
	ds_read_b128 v[220:223], v175 offset:20480
	ds_read_b128 v[224:227], v175 offset:21504
	ds_read_b128 v[228:231], v175 offset:22528
	ds_read_b128 v[232:235], v175 offset:23552
	global_load_lds_dwordx4 v138, s[2:3]
	s_add_i32 m0, s74, 0x2000
	s_add_u32 s74, s2, 0x80000
	s_addc_u32 s75, s3, 0
	s_add_i32 s76, s68, s33
	global_load_lds_dwordx4 v142, s[2:3]
	s_mov_b32 m0, s76
	s_nop 0
	global_load_lds_dwordx4 v138, s[74:75]
	s_add_i32 m0, s76, 0x2000
	s_nop 0
	global_load_lds_dwordx4 v142, s[74:75]
	s_mov_b32 m0, s29
	s_nop 0
	global_load_lds_dwordx4 v136, s[4:5]
	s_mov_b32 m0, s34
	s_nop 0
	global_load_lds_dwordx4 v140, s[4:5]
	s_waitcnt vmcnt(8)
	s_waitcnt lgkmcnt(0)
	s_barrier
	s_setprio 1
	s_waitcnt lgkmcnt(0)
	v_mfma_f32_16x16x32_bf16 v[60:63], v[128:131], v[204:207], v[60:63]
	v_mfma_f32_16x16x32_bf16 v[56:59], v[156:159], v[204:207], v[56:59]
	v_mfma_f32_16x16x32_bf16 v[52:55], v[128:131], v[212:215], v[52:55]
	v_mfma_f32_16x16x32_bf16 v[48:51], v[156:159], v[212:215], v[48:51]
	v_mfma_f32_16x16x32_bf16 v[36:39], v[128:131], v[220:223], v[36:39]
	v_mfma_f32_16x16x32_bf16 v[32:35], v[156:159], v[220:223], v[32:35]
	v_mfma_f32_16x16x32_bf16 v[20:23], v[128:131], v[228:231], v[20:23]
	v_mfma_f32_16x16x32_bf16 v[16:19], v[156:159], v[228:231], v[16:19]
	v_mfma_f32_16x16x32_bf16 v[60:63], v[132:135], v[208:211], v[60:63]
	v_mfma_f32_16x16x32_bf16 v[56:59], v[180:183], v[208:211], v[56:59]
	v_mfma_f32_16x16x32_bf16 v[52:55], v[132:135], v[216:219], v[52:55]
	v_mfma_f32_16x16x32_bf16 v[48:51], v[180:183], v[216:219], v[48:51]
	v_mfma_f32_16x16x32_bf16 v[36:39], v[132:135], v[224:227], v[36:39]
	v_mfma_f32_16x16x32_bf16 v[32:35], v[180:183], v[224:227], v[32:35]
	v_mfma_f32_16x16x32_bf16 v[20:23], v[132:135], v[232:235], v[20:23]
	v_mfma_f32_16x16x32_bf16 v[16:19], v[180:183], v[232:235], v[16:19]
	s_setprio 0
	s_setprio 1
	v_mfma_f32_16x16x32_bf16 v[44:47], v[184:187], v[204:207], v[44:47]
	v_mfma_f32_16x16x32_bf16 v[40:43], v[192:195], v[204:207], v[40:43]
	v_mfma_f32_16x16x32_bf16 v[28:31], v[184:187], v[212:215], v[28:31]
	v_mfma_f32_16x16x32_bf16 v[24:27], v[192:195], v[212:215], v[24:27]
	v_mfma_f32_16x16x32_bf16 v[12:15], v[184:187], v[220:223], v[12:15]
	v_mfma_f32_16x16x32_bf16 v[8:11], v[192:195], v[220:223], v[8:11]
	v_mfma_f32_16x16x32_bf16 v[4:7], v[184:187], v[228:231], v[4:7]
	v_mfma_f32_16x16x32_bf16 v[0:3], v[192:195], v[228:231], v[0:3]
	v_mfma_f32_16x16x32_bf16 v[44:47], v[188:191], v[208:211], v[44:47]
	v_mfma_f32_16x16x32_bf16 v[40:43], v[200:203], v[208:211], v[40:43]
	v_mfma_f32_16x16x32_bf16 v[28:31], v[188:191], v[216:219], v[28:31]
	v_mfma_f32_16x16x32_bf16 v[24:27], v[200:203], v[216:219], v[24:27]
	v_mfma_f32_16x16x32_bf16 v[12:15], v[188:191], v[224:227], v[12:15]
	v_mfma_f32_16x16x32_bf16 v[8:11], v[200:203], v[224:227], v[8:11]
	v_mfma_f32_16x16x32_bf16 v[4:7], v[188:191], v[232:235], v[4:7]
	v_mfma_f32_16x16x32_bf16 v[0:3], v[200:203], v[232:235], v[0:3]
	s_setprio 0
	s_barrier
; #define PG8_STAGE(bufoff, gbase, voff) do { _Pragma("unroll") for (int _i = 0; _i < 2; ++_i) \
;         __builtin_amdgcn_global_load_lds((const unsigned*)((const char*)(gbase) + (voff)[_i]), (PG8_LAS unsigned*)(lds + (bufoff) + ldsw + _i * 8192), 16, 0, 0); } while (0)
; #define PG8_LDA(dst, b, h) do { _Pragma("unroll") for (int m = 0; m < 4; ++m) _Pragma("unroll") for (int k = 0; k < 2; ++k) dst[m][k] = *(const PG8_LAS bf16x8*)(lds + PG8_SA(b, h) + aoff + m * 2048 + k * 1024); } while (0)
; #define PG8_MMA(ai, bj, At, Bt) do { __builtin_amdgcn_s_setprio(1); _Pragma("unroll") for (int m = 0; m < 4; ++m) _Pragma("unroll") for (int n = 0; n < 2; ++n) _Pragma("unroll") for (int k = 0; k < 2; ++k) \
;         acc[ai][bj][m][n] = __builtin_amdgcn_mfma_f32_16x16x32_bf16(Bt[n][k], At[m][k], acc[ai][bj][m][n], 0, 0, 0); __builtin_amdgcn_s_setprio(0); } while (0)
; #define PG8_WAIT_V(n) asm volatile("s_waitcnt vmcnt(" #n ")" ::: "memory")
; #define PG8_WAIT_L(n) asm volatile("s_waitcnt lgkmcnt(" #n ")" ::: "memory")
; #define PG8_BAR __builtin_amdgcn_s_barrier()
; #define PG8_SCHED __builtin_amdgcn_sched_barrier(0)
; template <class Epi, class Sched, bool ALIGN_EPI = false, bool SP2 = false>
; __device__ __forceinline__ void gemm_phase(PG8_LAS unsigned char* lds, const Gemm g, const Sched& S, const Epi& E) {
;     ...
;         for (int t = 0; t < nt; t += 2) {
;             const bool last = (t == nt - 2);
;             const char* a1 = cA + (size_t)(t + 1) * kstep;
;             const char* a2 = last ? nA : cA + (size_t)(t + 2) * kstep; const char* b2 = last ? nB : cB + (size_t)(t + 2) * kstep;
;     ...
;             PG8_WAIT_V(8); PG8_WAIT_L(0); PG8_BAR; PG8_MMA(0, 0, At, B0); PG8_MMA(0, 1, At, B1); PG8_BAR; PG8_SCHED;
;             PG8_LDA(At, 1, 1); PG8_STAGE(PG8_SB(1, 0), b3, voffB); PG8_STAGE(PG8_SB(1, 1), b3 + hstep, voffB); PG8_STAGE(PG8_SA(1, 0), a3, voffA);
;             PG8_WAIT_V(8); PG8_WAIT_L(0); PG8_BAR; PG8_MMA(1, 0, At, B0); PG8_MMA(1, 1, At, B1); PG8_BAR; PG8_SCHED;
	s_add_i32 s74, 0, 0x18000
	v_add_u32_e32 v144, s74, v161
	s_add_i32 s75, 0, 0x1c000
	ds_read_b128 v[128:131], v144
	ds_read_b128 v[132:135], v144 offset:1024
	ds_read_b128 v[156:159], v144 offset:2048
	ds_read_b128 v[180:183], v144 offset:3072
	v_add_u32_e32 v144, s75, v161
	ds_read_b128 v[184:187], v144
	ds_read_b128 v[188:191], v144 offset:1024
	ds_read_b128 v[192:195], v144 offset:2048
	ds_read_b128 v[200:203], v144 offset:3072
	s_add_u32 s4, s4, 0x80000
	s_addc_u32 s5, s5, 0
	s_mov_b32 m0, s35
	ds_read_b128 v[204:207], v175 offset:32768
	ds_read_b128 v[208:211], v175 offset:33792
	ds_read_b128 v[212:215], v175 offset:34816
	ds_read_b128 v[216:219], v175 offset:35840
	ds_read_b128 v[220:223], v175 offset:36864
	ds_read_b128 v[224:227], v175 offset:37888
	ds_read_b128 v[228:231], v175 offset:38912
	ds_read_b128 v[232:235], v175 offset:39936
	global_load_lds_dwordx4 v136, s[4:5]
	s_mov_b32 m0, s36
	s_nop 0
	global_load_lds_dwordx4 v140, s[4:5]
	s_waitcnt vmcnt(8)
	s_waitcnt lgkmcnt(0)
	s_barrier
	s_setprio 1
	s_waitcnt lgkmcnt(0)
	v_mfma_f32_16x16x32_bf16 v[124:127], v[128:131], v[204:207], v[124:127]
	v_mfma_f32_16x16x32_bf16 v[120:123], v[156:159], v[204:207], v[120:123]
	v_mfma_f32_16x16x32_bf16 v[116:119], v[128:131], v[212:215], v[116:119]
	v_mfma_f32_16x16x32_bf16 v[112:115], v[156:159], v[212:215], v[112:115]
	v_mfma_f32_16x16x32_bf16 v[100:103], v[128:131], v[220:223], v[100:103]
	v_mfma_f32_16x16x32_bf16 v[96:99], v[156:159], v[220:223], v[96:99]
	v_mfma_f32_16x16x32_bf16 v[84:87], v[128:131], v[228:231], v[84:87]
	v_mfma_f32_16x16x32_bf16 v[80:83], v[156:159], v[228:231], v[80:83]
	v_mfma_f32_16x16x32_bf16 v[124:127], v[132:135], v[208:211], v[124:127]
	v_mfma_f32_16x16x32_bf16 v[120:123], v[180:183], v[208:211], v[120:123]
	v_mfma_f32_16x16x32_bf16 v[116:119], v[132:135], v[216:219], v[116:119]
	v_mfma_f32_16x16x32_bf16 v[112:115], v[180:183], v[216:219], v[112:115]
	v_mfma_f32_16x16x32_bf16 v[100:103], v[132:135], v[224:227], v[100:103]
	v_mfma_f32_16x16x32_bf16 v[96:99], v[180:183], v[224:227], v[96:99]
	v_mfma_f32_16x16x32_bf16 v[84:87], v[132:135], v[232:235], v[84:87]
	v_mfma_f32_16x16x32_bf16 v[80:83], v[180:183], v[232:235], v[80:83]
	s_setprio 0
	s_setprio 1
	v_mfma_f32_16x16x32_bf16 v[108:111], v[184:187], v[204:207], v[108:111]
	v_mfma_f32_16x16x32_bf16 v[104:107], v[192:195], v[204:207], v[104:107]
	v_mfma_f32_16x16x32_bf16 v[92:95], v[184:187], v[212:215], v[92:95]
	v_mfma_f32_16x16x32_bf16 v[88:91], v[192:195], v[212:215], v[88:91]
	v_mfma_f32_16x16x32_bf16 v[76:79], v[184:187], v[220:223], v[76:79]
	v_mfma_f32_16x16x32_bf16 v[72:75], v[192:195], v[220:223], v[72:75]
	v_mfma_f32_16x16x32_bf16 v[68:71], v[184:187], v[228:231], v[68:71]
	v_mfma_f32_16x16x32_bf16 v[64:67], v[192:195], v[228:231], v[64:67]
	v_mfma_f32_16x16x32_bf16 v[108:111], v[188:191], v[208:211], v[108:111]
	v_mfma_f32_16x16x32_bf16 v[104:107], v[200:203], v[208:211], v[104:107]
	v_mfma_f32_16x16x32_bf16 v[92:95], v[188:191], v[216:219], v[92:95]
	v_mfma_f32_16x16x32_bf16 v[88:91], v[200:203], v[216:219], v[88:91]
	v_mfma_f32_16x16x32_bf16 v[76:79], v[188:191], v[224:227], v[76:79]
	v_mfma_f32_16x16x32_bf16 v[72:75], v[200:203], v[224:227], v[72:75]
	v_mfma_f32_16x16x32_bf16 v[68:71], v[188:191], v[232:235], v[68:71]
	v_mfma_f32_16x16x32_bf16 v[64:67], v[200:203], v[232:235], v[64:67]
	s_setprio 0
	s_barrier
	s_add_i32 s4, s74, s33
	s_mov_b32 m0, s4
	ds_read_b128 v[204:207], v175 offset:49152
	ds_read_b128 v[208:211], v175 offset:50176
	ds_read_b128 v[212:215], v175 offset:51200
	ds_read_b128 v[216:219], v175 offset:52224
	ds_read_b128 v[220:223], v175 offset:53248
	ds_read_b128 v[224:227], v175 offset:54272
	ds_read_b128 v[228:231], v175 offset:55296
	ds_read_b128 v[232:235], v175 offset:56320
	global_load_lds_dwordx4 v138, s[98:99]
	s_add_i32 m0, s4, 0x2000
	s_add_u32 s2, s2, 0x80080
	s_addc_u32 s3, s3, 0
	s_add_i32 s4, s75, s33
	global_load_lds_dwordx4 v142, s[98:99]
	s_mov_b32 m0, s4
	s_nop 0
	global_load_lds_dwordx4 v138, s[2:3]
	s_add_i32 m0, s4, 0x2000
	s_nop 0
	global_load_lds_dwordx4 v142, s[2:3]
	s_mov_b32 m0, s41
	s_nop 0
	global_load_lds_dwordx4 v136, s[100:101]
	s_mov_b32 m0, s42
	s_nop 0
	global_load_lds_dwordx4 v140, s[100:101]
	s_waitcnt vmcnt(8)
	s_waitcnt lgkmcnt(0)
	s_barrier
	s_setprio 1
	s_waitcnt lgkmcnt(0)
	v_mfma_f32_16x16x32_bf16 v[60:63], v[128:131], v[204:207], v[60:63]
	v_mfma_f32_16x16x32_bf16 v[56:59], v[156:159], v[204:207], v[56:59]
	v_mfma_f32_16x16x32_bf16 v[52:55], v[128:131], v[212:215], v[52:55]
	v_mfma_f32_16x16x32_bf16 v[48:51], v[156:159], v[212:215], v[48:51]
	v_mfma_f32_16x16x32_bf16 v[36:39], v[128:131], v[220:223], v[36:39]
	v_mfma_f32_16x16x32_bf16 v[32:35], v[156:159], v[220:223], v[32:35]
	v_mfma_f32_16x16x32_bf16 v[20:23], v[128:131], v[228:231], v[20:23]
	v_mfma_f32_16x16x32_bf16 v[16:19], v[156:159], v[228:231], v[16:19]
	v_mfma_f32_16x16x32_bf16 v[60:63], v[132:135], v[208:211], v[60:63]
	v_mfma_f32_16x16x32_bf16 v[56:59], v[180:183], v[208:211], v[56:59]
	v_mfma_f32_16x16x32_bf16 v[52:55], v[132:135], v[216:219], v[52:55]
	v_mfma_f32_16x16x32_bf16 v[48:51], v[180:183], v[216:219], v[48:51]
	v_mfma_f32_16x16x32_bf16 v[36:39], v[132:135], v[224:227], v[36:39]
	v_mfma_f32_16x16x32_bf16 v[32:35], v[180:183], v[224:227], v[32:35]
	v_mfma_f32_16x16x32_bf16 v[20:23], v[132:135], v[232:235], v[20:23]
	v_mfma_f32_16x16x32_bf16 v[16:19], v[180:183], v[232:235], v[16:19]
	s_setprio 0
	s_setprio 1
	v_mfma_f32_16x16x32_bf16 v[44:47], v[184:187], v[204:207], v[44:47]
	v_mfma_f32_16x16x32_bf16 v[40:43], v[192:195], v[204:207], v[40:43]
	v_mfma_f32_16x16x32_bf16 v[28:31], v[184:187], v[212:215], v[28:31]
	v_mfma_f32_16x16x32_bf16 v[24:27], v[192:195], v[212:215], v[24:27]
	v_mfma_f32_16x16x32_bf16 v[12:15], v[184:187], v[220:223], v[12:15]
	v_mfma_f32_16x16x32_bf16 v[8:11], v[192:195], v[220:223], v[8:11]
	v_mfma_f32_16x16x32_bf16 v[4:7], v[184:187], v[228:231], v[4:7]
	v_mfma_f32_16x16x32_bf16 v[0:3], v[192:195], v[228:231], v[0:3]
	v_mfma_f32_16x16x32_bf16 v[44:47], v[188:191], v[208:211], v[44:47]
	v_mfma_f32_16x16x32_bf16 v[40:43], v[200:203], v[208:211], v[40:43]
	v_mfma_f32_16x16x32_bf16 v[28:31], v[188:191], v[216:219], v[28:31]
	v_mfma_f32_16x16x32_bf16 v[24:27], v[200:203], v[216:219], v[24:27]
	v_mfma_f32_16x16x32_bf16 v[12:15], v[188:191], v[224:227], v[12:15]
	v_mfma_f32_16x16x32_bf16 v[8:11], v[200:203], v[224:227], v[8:11]
	v_mfma_f32_16x16x32_bf16 v[4:7], v[188:191], v[232:235], v[4:7]
	v_mfma_f32_16x16x32_bf16 v[0:3], v[200:203], v[232:235], v[0:3]
	s_setprio 0
	s_barrier
	s_add_i32 s73, s73, 2
	s_add_u32 s30, s30, 0x100
	s_addc_u32 s31, s31, 0
	s_add_u32 s71, s71, 0x100
	s_addc_u32 s72, s72, 0
	s_cmp_gt_u32 s73, 29
	s_cbranch_scc0 .LBB0_104
	s_and_b64 vcc, exec, s[16:17]
	s_cbranch_vccz .LBB0_107
	s_barrier

; #define PG8_STAGE(bufoff, gbase, voff) do { _Pragma("unroll") for (int _i = 0; _i < 2; ++_i) \
;         __builtin_amdgcn_global_load_lds((const unsigned*)((const char*)(gbase) + (voff)[_i]), (PG8_LAS unsigned*)(lds + (bufoff) + ldsw + _i * 8192), 16, 0, 0); } while (0)
; #define PG8_LDA(dst, b, h) do { _Pragma("unroll") for (int m = 0; m < 4; ++m) _Pragma("unroll") for (int k = 0; k < 2; ++k) dst[m][k] = *(const PG8_LAS bf16x8*)(lds + PG8_SA(b, h) + aoff + m * 2048 + k * 1024); } while (0)
; #define PG8_LDB(dst, b, h) do { _Pragma("unroll") for (int n = 0; n < 2; ++n) _Pragma("unroll") for (int k = 0; k < 2; ++k) dst[n][k] = *(const PG8_LAS bf16x8*)(lds + PG8_SB(b, h) + boff + n * 2048 + k * 1024); } while (0)
; #define PG8_MMA(ai, bj, At, Bt) do { __builtin_amdgcn_s_setprio(1); _Pragma("unroll") for (int m = 0; m < 4; ++m) _Pragma("unroll") for (int n = 0; n < 2; ++n) _Pragma("unroll") for (int k = 0; k < 2; ++k) \
;         acc[ai][bj][m][n] = __builtin_amdgcn_mfma_f32_16x16x32_bf16(Bt[n][k], At[m][k], acc[ai][bj][m][n], 0, 0, 0); __builtin_amdgcn_s_setprio(0); } while (0)
; #define PG8_WAIT_V(n) asm volatile("s_waitcnt vmcnt(" #n ")" ::: "memory")
; #define PG8_WAIT_L(n) asm volatile("s_waitcnt lgkmcnt(" #n ")" ::: "memory")
; #define PG8_BAR __builtin_amdgcn_s_barrier()
; #define PG8_SCHED __builtin_amdgcn_sched_barrier(0)
; template <class Epi, class Sched, bool ALIGN_EPI = false, bool SP2 = false>
; __device__ __forceinline__ void gemm_phase(PG8_LAS unsigned char* lds, const Gemm g, const Sched& S, const Epi& E) {
;     ...
;             PG8_LDB(B0, 0, 0); PG8_LDB(B1, 0, 1); PG8_SCHED; PG8_LDA(At, 0, 0); PG8_STAGE(PG8_SA(1, 1), a1 + hstep, voffA);
;             PG8_WAIT_V(8); PG8_WAIT_L(0); PG8_BAR; PG8_MMA(0, 0, At, B0); PG8_MMA(0, 1, At, B1); PG8_BAR; PG8_SCHED;
;             PG8_LDA(At, 0, 1); PG8_STAGE(PG8_SB(0, 0), b2, voffB); PG8_STAGE(PG8_SB(0, 1), b2 + hstep, voffB); PG8_STAGE(PG8_SA(0, 0), a2, voffA);
;             PG8_WAIT_V(8); PG8_WAIT_L(0); PG8_BAR; PG8_MMA(1, 0, At, B0); PG8_MMA(1, 1, At, B1); PG8_BAR; PG8_SCHED;
.LBB0_527:
	ds_read_b128 v[144:147], v158
	ds_read_b128 v[162:165], v158 offset:1024
	ds_read_b128 v[166:169], v158 offset:2048
	ds_read_b128 v[170:173], v158 offset:3072
	ds_read_b128 v[174:177], v159
	ds_read_b128 v[178:181], v159 offset:1024
	ds_read_b128 v[182:185], v159 offset:2048
	ds_read_b128 v[186:189], v159 offset:3072
	s_add_u32 s2, s28, 0xfff80080
	s_addc_u32 s3, s29, -1
	s_cmp_eq_u32 s58, 28
	s_cselect_b32 s31, s21, s3
	s_cselect_b32 s30, s27, s2
	s_cselect_b32 s3, s19, s53
	s_cselect_b32 s2, s51, s52
	s_add_i32 m0, s34, 0xc000
	ds_read_b128 v[190:193], v160
	ds_read_b128 v[194:197], v160 offset:1024
	ds_read_b128 v[200:203], v160 offset:2048
	ds_read_b128 v[204:207], v160 offset:3072
	ds_read_b128 v[208:211], v160 offset:4096
	ds_read_b128 v[212:215], v160 offset:5120
	ds_read_b128 v[216:219], v160 offset:6144
	ds_read_b128 v[220:223], v160 offset:7168
	global_load_lds_dwordx4 v136, s[28:29]
	s_add_i32 m0, s34, 0xe000
	s_nop 0
	global_load_lds_dwordx4 v138, s[28:29]
	s_waitcnt vmcnt(8)
	s_waitcnt lgkmcnt(0)
	s_barrier
	s_setprio 1
	s_waitcnt lgkmcnt(0)
	v_mfma_f32_16x16x32_bf16 v[124:127], v[144:147], v[190:193], v[124:127]
	v_mfma_f32_16x16x32_bf16 v[120:123], v[166:169], v[190:193], v[120:123]
	v_mfma_f32_16x16x32_bf16 v[108:111], v[144:147], v[200:203], v[108:111]
	v_mfma_f32_16x16x32_bf16 v[104:107], v[166:169], v[200:203], v[104:107]
	v_mfma_f32_16x16x32_bf16 v[92:95], v[144:147], v[208:211], v[92:95]
	v_mfma_f32_16x16x32_bf16 v[88:91], v[166:169], v[208:211], v[88:91]
	v_mfma_f32_16x16x32_bf16 v[76:79], v[144:147], v[216:219], v[76:79]
	v_mfma_f32_16x16x32_bf16 v[72:75], v[166:169], v[216:219], v[72:75]
	v_mfma_f32_16x16x32_bf16 v[124:127], v[162:165], v[194:197], v[124:127]
	v_mfma_f32_16x16x32_bf16 v[120:123], v[170:173], v[194:197], v[120:123]
	v_mfma_f32_16x16x32_bf16 v[108:111], v[162:165], v[204:207], v[108:111]
	v_mfma_f32_16x16x32_bf16 v[104:107], v[170:173], v[204:207], v[104:107]
	v_mfma_f32_16x16x32_bf16 v[92:95], v[162:165], v[212:215], v[92:95]
	v_mfma_f32_16x16x32_bf16 v[88:91], v[170:173], v[212:215], v[88:91]
	v_mfma_f32_16x16x32_bf16 v[76:79], v[162:165], v[220:223], v[76:79]
	v_mfma_f32_16x16x32_bf16 v[72:75], v[170:173], v[220:223], v[72:75]
	s_setprio 0
	s_setprio 1
	v_mfma_f32_16x16x32_bf16 v[116:119], v[174:177], v[190:193], v[116:119]
	v_mfma_f32_16x16x32_bf16 v[112:115], v[182:185], v[190:193], v[112:115]
	v_mfma_f32_16x16x32_bf16 v[100:103], v[174:177], v[200:203], v[100:103]
	v_mfma_f32_16x16x32_bf16 v[96:99], v[182:185], v[200:203], v[96:99]
	v_mfma_f32_16x16x32_bf16 v[84:87], v[174:177], v[208:211], v[84:87]
	v_mfma_f32_16x16x32_bf16 v[80:83], v[182:185], v[208:211], v[80:83]
	v_mfma_f32_16x16x32_bf16 v[68:71], v[174:177], v[216:219], v[68:71]
	v_mfma_f32_16x16x32_bf16 v[64:67], v[182:185], v[216:219], v[64:67]
	v_mfma_f32_16x16x32_bf16 v[116:119], v[178:181], v[194:197], v[116:119]
	v_mfma_f32_16x16x32_bf16 v[112:115], v[186:189], v[194:197], v[112:115]
	v_mfma_f32_16x16x32_bf16 v[100:103], v[178:181], v[204:207], v[100:103]
	v_mfma_f32_16x16x32_bf16 v[96:99], v[186:189], v[204:207], v[96:99]
	v_mfma_f32_16x16x32_bf16 v[84:87], v[178:181], v[212:215], v[84:87]
	v_mfma_f32_16x16x32_bf16 v[80:83], v[186:189], v[212:215], v[80:83]
	v_mfma_f32_16x16x32_bf16 v[68:71], v[178:181], v[220:223], v[68:71]
	v_mfma_f32_16x16x32_bf16 v[64:67], v[186:189], v[220:223], v[64:67]
	s_setprio 0
	s_barrier
	s_add_u32 s98, s2, s14
	s_addc_u32 s99, s3, s15
	s_add_u32 s100, s30, s14
	s_addc_u32 s101, s31, s15
	s_add_i32 s59, s48, s33
	s_mov_b32 m0, s59
	ds_read_b128 v[190:193], v160 offset:16384
	ds_read_b128 v[194:197], v160 offset:17408
	ds_read_b128 v[200:203], v160 offset:18432
	ds_read_b128 v[204:207], v160 offset:19456
	ds_read_b128 v[208:211], v160 offset:20480
	ds_read_b128 v[212:215], v160 offset:21504
	ds_read_b128 v[216:219], v160 offset:22528
	ds_read_b128 v[220:223], v160 offset:23552
	global_load_lds_dwordx4 v130, s[2:3]
	s_add_i32 m0, s59, 0x2000
	s_add_u32 s68, s2, 0x80000
	s_addc_u32 s69, s3, 0
	s_add_i32 s59, s49, s33
	global_load_lds_dwordx4 v134, s[2:3]
	s_mov_b32 m0, s59
	s_nop 0
	global_load_lds_dwordx4 v130, s[68:69]
	s_add_i32 m0, s59, 0x2000
	s_nop 0
	global_load_lds_dwordx4 v134, s[68:69]
	s_mov_b32 m0, s34
	s_nop 0
	global_load_lds_dwordx4 v128, s[30:31]
	s_mov_b32 m0, s35
	s_nop 0
	global_load_lds_dwordx4 v132, s[30:31]
	s_waitcnt vmcnt(8)
	s_waitcnt lgkmcnt(0)
	s_barrier
	s_setprio 1
	s_waitcnt lgkmcnt(0)
	v_mfma_f32_16x16x32_bf16 v[60:63], v[144:147], v[190:193], v[60:63]
	v_mfma_f32_16x16x32_bf16 v[56:59], v[166:169], v[190:193], v[56:59]
	v_mfma_f32_16x16x32_bf16 v[44:47], v[144:147], v[200:203], v[44:47]
	v_mfma_f32_16x16x32_bf16 v[40:43], v[166:169], v[200:203], v[40:43]
	v_mfma_f32_16x16x32_bf16 v[28:31], v[144:147], v[208:211], v[28:31]
	v_mfma_f32_16x16x32_bf16 v[24:27], v[166:169], v[208:211], v[24:27]
	v_mfma_f32_16x16x32_bf16 v[12:15], v[144:147], v[216:219], v[12:15]
	v_mfma_f32_16x16x32_bf16 v[8:11], v[166:169], v[216:219], v[8:11]
	v_mfma_f32_16x16x32_bf16 v[60:63], v[162:165], v[194:197], v[60:63]
	v_mfma_f32_16x16x32_bf16 v[56:59], v[170:173], v[194:197], v[56:59]
	v_mfma_f32_16x16x32_bf16 v[44:47], v[162:165], v[204:207], v[44:47]
	v_mfma_f32_16x16x32_bf16 v[40:43], v[170:173], v[204:207], v[40:43]
	v_mfma_f32_16x16x32_bf16 v[28:31], v[162:165], v[212:215], v[28:31]
	v_mfma_f32_16x16x32_bf16 v[24:27], v[170:173], v[212:215], v[24:27]
	v_mfma_f32_16x16x32_bf16 v[12:15], v[162:165], v[220:223], v[12:15]
	v_mfma_f32_16x16x32_bf16 v[8:11], v[170:173], v[220:223], v[8:11]
	s_setprio 0
	s_setprio 1
	v_mfma_f32_16x16x32_bf16 v[52:55], v[174:177], v[190:193], v[52:55]
	v_mfma_f32_16x16x32_bf16 v[48:51], v[182:185], v[190:193], v[48:51]
	v_mfma_f32_16x16x32_bf16 v[36:39], v[174:177], v[200:203], v[36:39]
	v_mfma_f32_16x16x32_bf16 v[32:35], v[182:185], v[200:203], v[32:35]
	v_mfma_f32_16x16x32_bf16 v[20:23], v[174:177], v[208:211], v[20:23]
	v_mfma_f32_16x16x32_bf16 v[16:19], v[182:185], v[208:211], v[16:19]
	v_mfma_f32_16x16x32_bf16 v[4:7], v[174:177], v[216:219], v[4:7]
	v_mfma_f32_16x16x32_bf16 v[0:3], v[182:185], v[216:219], v[0:3]
	v_mfma_f32_16x16x32_bf16 v[52:55], v[178:181], v[194:197], v[52:55]
	v_mfma_f32_16x16x32_bf16 v[48:51], v[186:189], v[194:197], v[48:51]
	v_mfma_f32_16x16x32_bf16 v[36:39], v[178:181], v[204:207], v[36:39]
	v_mfma_f32_16x16x32_bf16 v[32:35], v[186:189], v[204:207], v[32:35]
	v_mfma_f32_16x16x32_bf16 v[20:23], v[178:181], v[212:215], v[20:23]
	v_mfma_f32_16x16x32_bf16 v[16:19], v[186:189], v[212:215], v[16:19]
	v_mfma_f32_16x16x32_bf16 v[4:7], v[178:181], v[220:223], v[4:7]
	v_mfma_f32_16x16x32_bf16 v[0:3], v[186:189], v[220:223], v[0:3]
	s_setprio 0
	s_barrier
; #define PG8_STAGE(bufoff, gbase, voff) do { _Pragma("unroll") for (int _i = 0; _i < 2; ++_i) \
;         __builtin_amdgcn_global_load_lds((const unsigned*)((const char*)(gbase) + (voff)[_i]), (PG8_LAS unsigned*)(lds + (bufoff) + ldsw + _i * 8192), 16, 0, 0); } while (0)
; #define PG8_LDA(dst, b, h) do { _Pragma("unroll") for (int m = 0; m < 4; ++m) _Pragma("unroll") for (int k = 0; k < 2; ++k) dst[m][k] = *(const PG8_LAS bf16x8*)(lds + PG8_SA(b, h) + aoff + m * 2048 + k * 1024); } while (0)
; #define PG8_LDB(dst, b, h) do { _Pragma("unroll") for (int n = 0; n < 2; ++n) _Pragma("unroll") for (int k = 0; k < 2; ++k) dst[n][k] = *(const PG8_LAS bf16x8*)(lds + PG8_SB(b, h) + boff + n * 2048 + k * 1024); } while (0)
; #define PG8_MMA(ai, bj, At, Bt) do { __builtin_amdgcn_s_setprio(1); _Pragma("unroll") for (int m = 0; m < 4; ++m) _Pragma("unroll") for (int n = 0; n < 2; ++n) _Pragma("unroll") for (int k = 0; k < 2; ++k) \
;         acc[ai][bj][m][n] = __builtin_amdgcn_mfma_f32_16x16x32_bf16(Bt[n][k], At[m][k], acc[ai][bj][m][n], 0, 0, 0); __builtin_amdgcn_s_setprio(0); } while (0)
; #define PG8_WAIT_V(n) asm volatile("s_waitcnt vmcnt(" #n ")" ::: "memory")
; #define PG8_WAIT_L(n) asm volatile("s_waitcnt lgkmcnt(" #n ")" ::: "memory")
; #define PG8_BAR __builtin_amdgcn_s_barrier()
; #define PG8_SCHED __builtin_amdgcn_sched_barrier(0)
; template <class Epi, class Sched, bool ALIGN_EPI = false, bool SP2 = false>
; __device__ __forceinline__ void gemm_phase(PG8_LAS unsigned char* lds, const Gemm g, const Sched& S, const Epi& E) {
;     ...
;             PG8_LDB(B0, 1, 0); PG8_LDB(B1, 1, 1); PG8_SCHED; PG8_LDA(At, 1, 0); PG8_STAGE(PG8_SA(0, 1), a2 + hstep, voffA);
;             PG8_WAIT_V(8); PG8_WAIT_L(0); PG8_BAR; PG8_MMA(0, 0, At, B0); PG8_MMA(0, 1, At, B1); PG8_BAR; PG8_SCHED;
;             PG8_LDA(At, 1, 1); PG8_STAGE(PG8_SB(1, 0), b3, voffB); PG8_STAGE(PG8_SB(1, 1), b3 + hstep, voffB); PG8_STAGE(PG8_SA(1, 0), a3, voffA);
;             PG8_WAIT_V(8); PG8_WAIT_L(0); PG8_BAR; PG8_MMA(1, 0, At, B0); PG8_MMA(1, 1, At, B1); PG8_BAR; PG8_SCHED;
;     ...
;         if constexpr (ALIGN_EPI) { if (wr == 0) PG8_BAR; }
;         if constexpr (!Epi::AFTER_DRAIN) { E(acc, cur, wr, wc, fr, fq); S.done(cur); }
;         if (!has_next) break;
	s_add_i32 s59, 0, 0x18000
	v_add_u32_e32 v155, s59, v156
	s_add_i32 s68, 0, 0x1c000
	ds_read_b128 v[144:147], v155
	ds_read_b128 v[162:165], v155 offset:1024
	ds_read_b128 v[166:169], v155 offset:2048
	ds_read_b128 v[170:173], v155 offset:3072
	v_add_u32_e32 v155, s68, v156
	ds_read_b128 v[174:177], v155
	ds_read_b128 v[178:181], v155 offset:1024
	ds_read_b128 v[182:185], v155 offset:2048
	ds_read_b128 v[186:189], v155 offset:3072
	s_add_u32 s30, s30, 0x80000
	s_addc_u32 s31, s31, 0
	s_mov_b32 m0, s36
	ds_read_b128 v[190:193], v160 offset:32768
	ds_read_b128 v[194:197], v160 offset:33792
	ds_read_b128 v[200:203], v160 offset:34816
	ds_read_b128 v[204:207], v160 offset:35840
	ds_read_b128 v[208:211], v160 offset:36864
	ds_read_b128 v[212:215], v160 offset:37888
	ds_read_b128 v[216:219], v160 offset:38912
	ds_read_b128 v[220:223], v160 offset:39936
	global_load_lds_dwordx4 v128, s[30:31]
	s_mov_b32 m0, s37
	s_nop 0
	global_load_lds_dwordx4 v132, s[30:31]
	s_waitcnt vmcnt(8)
	s_waitcnt lgkmcnt(0)
	s_barrier
	s_setprio 1
	s_waitcnt lgkmcnt(0)
	v_mfma_f32_16x16x32_bf16 v[124:127], v[144:147], v[190:193], v[124:127]
	v_mfma_f32_16x16x32_bf16 v[120:123], v[166:169], v[190:193], v[120:123]
	v_mfma_f32_16x16x32_bf16 v[108:111], v[144:147], v[200:203], v[108:111]
	v_mfma_f32_16x16x32_bf16 v[104:107], v[166:169], v[200:203], v[104:107]
	v_mfma_f32_16x16x32_bf16 v[92:95], v[144:147], v[208:211], v[92:95]
	v_mfma_f32_16x16x32_bf16 v[88:91], v[166:169], v[208:211], v[88:91]
	v_mfma_f32_16x16x32_bf16 v[76:79], v[144:147], v[216:219], v[76:79]
	v_mfma_f32_16x16x32_bf16 v[72:75], v[166:169], v[216:219], v[72:75]
	v_mfma_f32_16x16x32_bf16 v[124:127], v[162:165], v[194:197], v[124:127]
	v_mfma_f32_16x16x32_bf16 v[120:123], v[170:173], v[194:197], v[120:123]
	v_mfma_f32_16x16x32_bf16 v[108:111], v[162:165], v[204:207], v[108:111]
	v_mfma_f32_16x16x32_bf16 v[104:107], v[170:173], v[204:207], v[104:107]
	v_mfma_f32_16x16x32_bf16 v[92:95], v[162:165], v[212:215], v[92:95]
	v_mfma_f32_16x16x32_bf16 v[88:91], v[170:173], v[212:215], v[88:91]
	v_mfma_f32_16x16x32_bf16 v[76:79], v[162:165], v[220:223], v[76:79]
	v_mfma_f32_16x16x32_bf16 v[72:75], v[170:173], v[220:223], v[72:75]
	s_setprio 0
	s_setprio 1
	v_mfma_f32_16x16x32_bf16 v[116:119], v[174:177], v[190:193], v[116:119]
	v_mfma_f32_16x16x32_bf16 v[112:115], v[182:185], v[190:193], v[112:115]
	v_mfma_f32_16x16x32_bf16 v[100:103], v[174:177], v[200:203], v[100:103]
	v_mfma_f32_16x16x32_bf16 v[96:99], v[182:185], v[200:203], v[96:99]
	v_mfma_f32_16x16x32_bf16 v[84:87], v[174:177], v[208:211], v[84:87]
	v_mfma_f32_16x16x32_bf16 v[80:83], v[182:185], v[208:211], v[80:83]
	v_mfma_f32_16x16x32_bf16 v[68:71], v[174:177], v[216:219], v[68:71]
	v_mfma_f32_16x16x32_bf16 v[64:67], v[182:185], v[216:219], v[64:67]
	v_mfma_f32_16x16x32_bf16 v[116:119], v[178:181], v[194:197], v[116:119]
	v_mfma_f32_16x16x32_bf16 v[112:115], v[186:189], v[194:197], v[112:115]
	v_mfma_f32_16x16x32_bf16 v[100:103], v[178:181], v[204:207], v[100:103]
	v_mfma_f32_16x16x32_bf16 v[96:99], v[186:189], v[204:207], v[96:99]
	v_mfma_f32_16x16x32_bf16 v[84:87], v[178:181], v[212:215], v[84:87]
	v_mfma_f32_16x16x32_bf16 v[80:83], v[186:189], v[212:215], v[80:83]
	v_mfma_f32_16x16x32_bf16 v[68:71], v[178:181], v[220:223], v[68:71]
	v_mfma_f32_16x16x32_bf16 v[64:67], v[186:189], v[220:223], v[64:67]
	s_setprio 0
	s_barrier
	s_add_i32 s30, s59, s33
	s_mov_b32 m0, s30
	ds_read_b128 v[190:193], v160 offset:49152
	ds_read_b128 v[194:197], v160 offset:50176
	ds_read_b128 v[200:203], v160 offset:51200
	ds_read_b128 v[204:207], v160 offset:52224
	ds_read_b128 v[208:211], v160 offset:53248
	ds_read_b128 v[212:215], v160 offset:54272
	ds_read_b128 v[216:219], v160 offset:55296
	ds_read_b128 v[220:223], v160 offset:56320
	global_load_lds_dwordx4 v130, s[98:99]
	s_add_i32 m0, s30, 0x2000
	s_add_u32 s2, s2, 0x80080
	s_addc_u32 s3, s3, 0
	s_add_i32 s30, s68, s33
	global_load_lds_dwordx4 v134, s[98:99]
	s_mov_b32 m0, s30
	s_nop 0
	global_load_lds_dwordx4 v130, s[2:3]
	s_add_i32 m0, s30, 0x2000
	s_nop 0
	global_load_lds_dwordx4 v134, s[2:3]
	s_mov_b32 m0, s41
	s_nop 0
	global_load_lds_dwordx4 v128, s[100:101]
	s_mov_b32 m0, s42
	s_nop 0
	global_load_lds_dwordx4 v132, s[100:101]
	s_waitcnt vmcnt(8)
	s_waitcnt lgkmcnt(0)
	s_barrier
	s_setprio 1
	s_waitcnt lgkmcnt(0)
	v_mfma_f32_16x16x32_bf16 v[60:63], v[144:147], v[190:193], v[60:63]
	v_mfma_f32_16x16x32_bf16 v[56:59], v[166:169], v[190:193], v[56:59]
	v_mfma_f32_16x16x32_bf16 v[44:47], v[144:147], v[200:203], v[44:47]
	v_mfma_f32_16x16x32_bf16 v[40:43], v[166:169], v[200:203], v[40:43]
	v_mfma_f32_16x16x32_bf16 v[28:31], v[144:147], v[208:211], v[28:31]
	v_mfma_f32_16x16x32_bf16 v[24:27], v[166:169], v[208:211], v[24:27]
	v_mfma_f32_16x16x32_bf16 v[12:15], v[144:147], v[216:219], v[12:15]
	v_mfma_f32_16x16x32_bf16 v[8:11], v[166:169], v[216:219], v[8:11]
	v_mfma_f32_16x16x32_bf16 v[60:63], v[162:165], v[194:197], v[60:63]
	v_mfma_f32_16x16x32_bf16 v[56:59], v[170:173], v[194:197], v[56:59]
	v_mfma_f32_16x16x32_bf16 v[44:47], v[162:165], v[204:207], v[44:47]
	v_mfma_f32_16x16x32_bf16 v[40:43], v[170:173], v[204:207], v[40:43]
	v_mfma_f32_16x16x32_bf16 v[28:31], v[162:165], v[212:215], v[28:31]
	v_mfma_f32_16x16x32_bf16 v[24:27], v[170:173], v[212:215], v[24:27]
	v_mfma_f32_16x16x32_bf16 v[12:15], v[162:165], v[220:223], v[12:15]
	v_mfma_f32_16x16x32_bf16 v[8:11], v[170:173], v[220:223], v[8:11]
	s_setprio 0
	s_setprio 1
	v_mfma_f32_16x16x32_bf16 v[52:55], v[174:177], v[190:193], v[52:55]
	v_mfma_f32_16x16x32_bf16 v[48:51], v[182:185], v[190:193], v[48:51]
	v_mfma_f32_16x16x32_bf16 v[36:39], v[174:177], v[200:203], v[36:39]
	v_mfma_f32_16x16x32_bf16 v[32:35], v[182:185], v[200:203], v[32:35]
	v_mfma_f32_16x16x32_bf16 v[20:23], v[174:177], v[208:211], v[20:23]
	v_mfma_f32_16x16x32_bf16 v[16:19], v[182:185], v[208:211], v[16:19]
	v_mfma_f32_16x16x32_bf16 v[4:7], v[174:177], v[216:219], v[4:7]
	v_mfma_f32_16x16x32_bf16 v[0:3], v[182:185], v[216:219], v[0:3]
	v_mfma_f32_16x16x32_bf16 v[52:55], v[178:181], v[194:197], v[52:55]
	v_mfma_f32_16x16x32_bf16 v[48:51], v[186:189], v[194:197], v[48:51]
	v_mfma_f32_16x16x32_bf16 v[36:39], v[178:181], v[204:207], v[36:39]
	v_mfma_f32_16x16x32_bf16 v[32:35], v[186:189], v[204:207], v[32:35]
	v_mfma_f32_16x16x32_bf16 v[20:23], v[178:181], v[212:215], v[20:23]
	v_mfma_f32_16x16x32_bf16 v[16:19], v[186:189], v[212:215], v[16:19]
	v_mfma_f32_16x16x32_bf16 v[4:7], v[178:181], v[220:223], v[4:7]
	v_mfma_f32_16x16x32_bf16 v[0:3], v[186:189], v[220:223], v[0:3]
	s_setprio 0
	s_barrier
	s_add_i32 s58, s58, 2
	s_add_u32 s28, s28, 0x100
	s_addc_u32 s29, s29, 0
	s_add_u32 s52, s52, 0x100
	s_addc_u32 s53, s53, 0
	s_cmp_gt_u32 s58, 29
	s_cbranch_scc0 .LBB0_527
	s_and_b64 vcc, exec, s[16:17]
	s_cbranch_vccz .LBB0_530
	s_barrier

; #define PG8_STAGE(bufoff, gbase, voff) do { _Pragma("unroll") for (int _i = 0; _i < 2; ++_i) \
;         __builtin_amdgcn_global_load_lds((const unsigned*)((const char*)(gbase) + (voff)[_i]), (PG8_LAS unsigned*)(lds + (bufoff) + ldsw + _i * 8192), 16, 0, 0); } while (0)
; #define PG8_LDA(dst, b, h) do { _Pragma("unroll") for (int m = 0; m < 4; ++m) _Pragma("unroll") for (int k = 0; k < 2; ++k) dst[m][k] = *(const PG8_LAS bf16x8*)(lds + PG8_SA(b, h) + aoff + m * 2048 + k * 1024); } while (0)
; #define PG8_LDB(dst, b, h) do { _Pragma("unroll") for (int n = 0; n < 2; ++n) _Pragma("unroll") for (int k = 0; k < 2; ++k) dst[n][k] = *(const PG8_LAS bf16x8*)(lds + PG8_SB(b, h) + boff + n * 2048 + k * 1024); } while (0)
; #define PG8_MMA(ai, bj, At, Bt) do { __builtin_amdgcn_s_setprio(1); _Pragma("unroll") for (int m = 0; m < 4; ++m) _Pragma("unroll") for (int n = 0; n < 2; ++n) _Pragma("unroll") for (int k = 0; k < 2; ++k) \
;         acc[ai][bj][m][n] = __builtin_amdgcn_mfma_f32_16x16x32_bf16(Bt[n][k], At[m][k], acc[ai][bj][m][n], 0, 0, 0); __builtin_amdgcn_s_setprio(0); } while (0)
; #define PG8_WAIT_V(n) asm volatile("s_waitcnt vmcnt(" #n ")" ::: "memory")
; #define PG8_WAIT_L(n) asm volatile("s_waitcnt lgkmcnt(" #n ")" ::: "memory")
; #define PG8_BAR __builtin_amdgcn_s_barrier()
; template <class Epi, class Sched, bool ALIGN_EPI = false, bool SP2 = false>
; __device__ __forceinline__ void gemm_phase(PG8_LAS unsigned char* lds, const Gemm g, const Sched& S, const Epi& E) {
;     ...
;             const char* a1 = cA + (size_t)(t + 1) * kstep;
;             const char* a2 = last ? nA : cA + (size_t)(t + 2) * kstep; const char* b2 = last ? nB : cB + (size_t)(t + 2) * kstep;
;             const char* a3 = a2 + kstep; const char* b3 = b2 + kstep;
;             if (last && has_next) S.a_ready(nxt);
;             if constexpr (SP2) {
;             PG8_LDB(B0, 0, 0); PG8_LDB(B1, 0, 1); PG8_SCHED; PG8_LDA(At, 0, 0); PG8_STAGE(PG8_SA(1, 1), a1 + hstep, voffA);
;             PG8_WAIT_V(8); PG8_WAIT_L(0); PG8_BAR; PG8_MMA(0, 0, At, B0); PG8_MMA(0, 1, At, B1); PG8_BAR; PG8_SCHED;
;             PG8_LDA(At, 0, 1); PG8_STAGE(PG8_SB(0, 0), b2, voffB); PG8_STAGE(PG8_SB(0, 1), b2 + hstep, voffB); PG8_STAGE(PG8_SA(0, 0), a2, voffA);
;             PG8_WAIT_V(8); PG8_WAIT_L(0); PG8_BAR; PG8_MMA(1, 0, At, B0); PG8_MMA(1, 1, At, B1); PG8_BAR; PG8_SCHED;
.LBB0_629:
	ds_read_b128 v[156:159], v151
	ds_read_b128 v[160:163], v151 offset:1024
	ds_read_b128 v[164:167], v151 offset:2048
	ds_read_b128 v[168:171], v151 offset:3072
	ds_read_b128 v[172:175], v152
	ds_read_b128 v[176:179], v152 offset:1024
	ds_read_b128 v[180:183], v152 offset:2048
	ds_read_b128 v[184:187], v152 offset:3072
	s_add_u32 s2, s30, 0xfff80080
	s_addc_u32 s3, s31, -1
	s_cmp_eq_u32 s58, 28
	s_cselect_b32 s35, s23, s3
	s_cselect_b32 s34, s52, s2
	s_cselect_b32 s3, s21, s57
	s_cselect_b32 s2, s53, s56
	s_add_i32 m0, s29, 0xc000
	ds_read_b128 v[188:191], v153
	ds_read_b128 v[192:195], v153 offset:1024
	ds_read_b128 v[200:203], v153 offset:2048
	ds_read_b128 v[204:207], v153 offset:3072
	ds_read_b128 v[208:211], v153 offset:4096
	ds_read_b128 v[212:215], v153 offset:5120
	ds_read_b128 v[216:219], v153 offset:6144
	ds_read_b128 v[220:223], v153 offset:7168
	global_load_lds_dwordx4 v136, s[30:31]
	s_add_i32 m0, s29, 0xe000
	s_nop 0
	global_load_lds_dwordx4 v138, s[30:31]
	s_waitcnt vmcnt(8)
	s_waitcnt lgkmcnt(0)
	s_barrier
	s_setprio 1
	s_waitcnt lgkmcnt(0)
	v_mfma_f32_16x16x32_bf16 v[124:127], v[156:159], v[188:191], v[124:127]
	v_mfma_f32_16x16x32_bf16 v[120:123], v[164:167], v[188:191], v[120:123]
	v_mfma_f32_16x16x32_bf16 v[108:111], v[156:159], v[200:203], v[108:111]
	v_mfma_f32_16x16x32_bf16 v[104:107], v[164:167], v[200:203], v[104:107]
	v_mfma_f32_16x16x32_bf16 v[92:95], v[156:159], v[208:211], v[92:95]
	v_mfma_f32_16x16x32_bf16 v[88:91], v[164:167], v[208:211], v[88:91]
	v_mfma_f32_16x16x32_bf16 v[76:79], v[156:159], v[216:219], v[76:79]
	v_mfma_f32_16x16x32_bf16 v[72:75], v[164:167], v[216:219], v[72:75]
	v_mfma_f32_16x16x32_bf16 v[124:127], v[160:163], v[192:195], v[124:127]
	v_mfma_f32_16x16x32_bf16 v[120:123], v[168:171], v[192:195], v[120:123]
	v_mfma_f32_16x16x32_bf16 v[108:111], v[160:163], v[204:207], v[108:111]
	v_mfma_f32_16x16x32_bf16 v[104:107], v[168:171], v[204:207], v[104:107]
	v_mfma_f32_16x16x32_bf16 v[92:95], v[160:163], v[212:215], v[92:95]
	v_mfma_f32_16x16x32_bf16 v[88:91], v[168:171], v[212:215], v[88:91]
	v_mfma_f32_16x16x32_bf16 v[76:79], v[160:163], v[220:223], v[76:79]
	v_mfma_f32_16x16x32_bf16 v[72:75], v[168:171], v[220:223], v[72:75]
	s_setprio 0
	s_setprio 1
	v_mfma_f32_16x16x32_bf16 v[116:119], v[172:175], v[188:191], v[116:119]
	v_mfma_f32_16x16x32_bf16 v[112:115], v[180:183], v[188:191], v[112:115]
	v_mfma_f32_16x16x32_bf16 v[100:103], v[172:175], v[200:203], v[100:103]
	v_mfma_f32_16x16x32_bf16 v[96:99], v[180:183], v[200:203], v[96:99]
	v_mfma_f32_16x16x32_bf16 v[84:87], v[172:175], v[208:211], v[84:87]
	v_mfma_f32_16x16x32_bf16 v[80:83], v[180:183], v[208:211], v[80:83]
	v_mfma_f32_16x16x32_bf16 v[68:71], v[172:175], v[216:219], v[68:71]
	v_mfma_f32_16x16x32_bf16 v[64:67], v[180:183], v[216:219], v[64:67]
	v_mfma_f32_16x16x32_bf16 v[116:119], v[176:179], v[192:195], v[116:119]
	v_mfma_f32_16x16x32_bf16 v[112:115], v[184:187], v[192:195], v[112:115]
	v_mfma_f32_16x16x32_bf16 v[100:103], v[176:179], v[204:207], v[100:103]
	v_mfma_f32_16x16x32_bf16 v[96:99], v[184:187], v[204:207], v[96:99]
	v_mfma_f32_16x16x32_bf16 v[84:87], v[176:179], v[212:215], v[84:87]
	v_mfma_f32_16x16x32_bf16 v[80:83], v[184:187], v[212:215], v[80:83]
	v_mfma_f32_16x16x32_bf16 v[68:71], v[176:179], v[220:223], v[68:71]
	v_mfma_f32_16x16x32_bf16 v[64:67], v[184:187], v[220:223], v[64:67]
	s_setprio 0
	s_barrier
	s_add_u32 s98, s2, s8
	s_addc_u32 s99, s3, s9
	s_add_u32 s100, s34, s8
	s_addc_u32 s101, s35, s9
	s_add_i32 s59, s45, s33
	s_mov_b32 m0, s59
	ds_read_b128 v[188:191], v153 offset:16384
	ds_read_b128 v[192:195], v153 offset:17408
	ds_read_b128 v[200:203], v153 offset:18432
	ds_read_b128 v[204:207], v153 offset:19456
	ds_read_b128 v[208:211], v153 offset:20480
	ds_read_b128 v[212:215], v153 offset:21504
	ds_read_b128 v[216:219], v153 offset:22528
	ds_read_b128 v[220:223], v153 offset:23552
	global_load_lds_dwordx4 v130, s[2:3]
	s_add_i32 m0, s59, 0x2000
	s_add_u32 s68, s2, 0x80000
	s_addc_u32 s69, s3, 0
	s_add_i32 s59, s46, s33
	global_load_lds_dwordx4 v134, s[2:3]
	s_mov_b32 m0, s59
	s_nop 0
	global_load_lds_dwordx4 v130, s[68:69]
	s_add_i32 m0, s59, 0x2000
	s_nop 0
	global_load_lds_dwordx4 v134, s[68:69]
	s_mov_b32 m0, s29
	s_nop 0
	global_load_lds_dwordx4 v128, s[34:35]
	s_mov_b32 m0, s37
	s_nop 0
	global_load_lds_dwordx4 v132, s[34:35]
	s_waitcnt vmcnt(8)
	s_waitcnt lgkmcnt(0)
	s_barrier
	s_setprio 1
	s_waitcnt lgkmcnt(0)
	v_mfma_f32_16x16x32_bf16 v[60:63], v[156:159], v[188:191], v[60:63]
	v_mfma_f32_16x16x32_bf16 v[56:59], v[164:167], v[188:191], v[56:59]
	v_mfma_f32_16x16x32_bf16 v[44:47], v[156:159], v[200:203], v[44:47]
	v_mfma_f32_16x16x32_bf16 v[40:43], v[164:167], v[200:203], v[40:43]
	v_mfma_f32_16x16x32_bf16 v[28:31], v[156:159], v[208:211], v[28:31]
	v_mfma_f32_16x16x32_bf16 v[24:27], v[164:167], v[208:211], v[24:27]
	v_mfma_f32_16x16x32_bf16 v[12:15], v[156:159], v[216:219], v[12:15]
	v_mfma_f32_16x16x32_bf16 v[8:11], v[164:167], v[216:219], v[8:11]
	v_mfma_f32_16x16x32_bf16 v[60:63], v[160:163], v[192:195], v[60:63]
	v_mfma_f32_16x16x32_bf16 v[56:59], v[168:171], v[192:195], v[56:59]
	v_mfma_f32_16x16x32_bf16 v[44:47], v[160:163], v[204:207], v[44:47]
	v_mfma_f32_16x16x32_bf16 v[40:43], v[168:171], v[204:207], v[40:43]
	v_mfma_f32_16x16x32_bf16 v[28:31], v[160:163], v[212:215], v[28:31]
	v_mfma_f32_16x16x32_bf16 v[24:27], v[168:171], v[212:215], v[24:27]
	v_mfma_f32_16x16x32_bf16 v[12:15], v[160:163], v[220:223], v[12:15]
	v_mfma_f32_16x16x32_bf16 v[8:11], v[168:171], v[220:223], v[8:11]
	s_setprio 0
	s_setprio 1
	v_mfma_f32_16x16x32_bf16 v[52:55], v[172:175], v[188:191], v[52:55]
	v_mfma_f32_16x16x32_bf16 v[48:51], v[180:183], v[188:191], v[48:51]
	v_mfma_f32_16x16x32_bf16 v[36:39], v[172:175], v[200:203], v[36:39]
	v_mfma_f32_16x16x32_bf16 v[32:35], v[180:183], v[200:203], v[32:35]
	v_mfma_f32_16x16x32_bf16 v[20:23], v[172:175], v[208:211], v[20:23]
	v_mfma_f32_16x16x32_bf16 v[16:19], v[180:183], v[208:211], v[16:19]
	v_mfma_f32_16x16x32_bf16 v[4:7], v[172:175], v[216:219], v[4:7]
	v_mfma_f32_16x16x32_bf16 v[0:3], v[180:183], v[216:219], v[0:3]
	v_mfma_f32_16x16x32_bf16 v[52:55], v[176:179], v[192:195], v[52:55]
	v_mfma_f32_16x16x32_bf16 v[48:51], v[184:187], v[192:195], v[48:51]
	v_mfma_f32_16x16x32_bf16 v[36:39], v[176:179], v[204:207], v[36:39]
	v_mfma_f32_16x16x32_bf16 v[32:35], v[184:187], v[204:207], v[32:35]
	v_mfma_f32_16x16x32_bf16 v[20:23], v[176:179], v[212:215], v[20:23]
	v_mfma_f32_16x16x32_bf16 v[16:19], v[184:187], v[212:215], v[16:19]
	v_mfma_f32_16x16x32_bf16 v[4:7], v[176:179], v[220:223], v[4:7]
	v_mfma_f32_16x16x32_bf16 v[0:3], v[184:187], v[220:223], v[0:3]
	s_setprio 0
	s_barrier
; #define PG8_STAGE(bufoff, gbase, voff) do { _Pragma("unroll") for (int _i = 0; _i < 2; ++_i) \
;         __builtin_amdgcn_global_load_lds((const unsigned*)((const char*)(gbase) + (voff)[_i]), (PG8_LAS unsigned*)(lds + (bufoff) + ldsw + _i * 8192), 16, 0, 0); } while (0)
; #define PG8_LDA(dst, b, h) do { _Pragma("unroll") for (int m = 0; m < 4; ++m) _Pragma("unroll") for (int k = 0; k < 2; ++k) dst[m][k] = *(const PG8_LAS bf16x8*)(lds + PG8_SA(b, h) + aoff + m * 2048 + k * 1024); } while (0)
; #define PG8_LDB(dst, b, h) do { _Pragma("unroll") for (int n = 0; n < 2; ++n) _Pragma("unroll") for (int k = 0; k < 2; ++k) dst[n][k] = *(const PG8_LAS bf16x8*)(lds + PG8_SB(b, h) + boff + n * 2048 + k * 1024); } while (0)
; #define PG8_MMA(ai, bj, At, Bt) do { __builtin_amdgcn_s_setprio(1); _Pragma("unroll") for (int m = 0; m < 4; ++m) _Pragma("unroll") for (int n = 0; n < 2; ++n) _Pragma("unroll") for (int k = 0; k < 2; ++k) \
;         acc[ai][bj][m][n] = __builtin_amdgcn_mfma_f32_16x16x32_bf16(Bt[n][k], At[m][k], acc[ai][bj][m][n], 0, 0, 0); __builtin_amdgcn_s_setprio(0); } while (0)
; #define PG8_WAIT_V(n) asm volatile("s_waitcnt vmcnt(" #n ")" ::: "memory")
; #define PG8_WAIT_L(n) asm volatile("s_waitcnt lgkmcnt(" #n ")" ::: "memory")
; #define PG8_BAR __builtin_amdgcn_s_barrier()
; #define PG8_SCHED __builtin_amdgcn_sched_barrier(0)
; template <class Epi, class Sched, bool ALIGN_EPI = false, bool SP2 = false>
; __device__ __forceinline__ void gemm_phase(PG8_LAS unsigned char* lds, const Gemm g, const Sched& S, const Epi& E) {
;     ...
;             PG8_LDB(B0, 1, 0); PG8_LDB(B1, 1, 1); PG8_SCHED; PG8_LDA(At, 1, 0); PG8_STAGE(PG8_SA(0, 1), a2 + hstep, voffA);
;             PG8_WAIT_V(8); PG8_WAIT_L(0); PG8_BAR; PG8_MMA(0, 0, At, B0); PG8_MMA(0, 1, At, B1); PG8_BAR; PG8_SCHED;
;             PG8_LDA(At, 1, 1); PG8_STAGE(PG8_SB(1, 0), b3, voffB); PG8_STAGE(PG8_SB(1, 1), b3 + hstep, voffB); PG8_STAGE(PG8_SA(1, 0), a3, voffA);
;             PG8_WAIT_V(8); PG8_WAIT_L(0); PG8_BAR; PG8_MMA(1, 0, At, B0); PG8_MMA(1, 1, At, B1); PG8_BAR; PG8_SCHED;
;     ...
;         if constexpr (ALIGN_EPI) { if (wr == 0) PG8_BAR; }
;         if constexpr (!Epi::AFTER_DRAIN) { E(acc, cur, wr, wc, fr, fq); S.done(cur); }
;         if (!has_next) break;
	s_add_i32 s59, 0, 0x18000
	s_add_i32 s68, 0, 0x1c000
	v_add_u32_e32 v168, s59, v149
	v_add_u32_e32 v184, s68, v149
	ds_read_b128 v[156:159], v168
	ds_read_b128 v[160:163], v168 offset:1024
	ds_read_b128 v[164:167], v168 offset:2048
	ds_read_b128 v[168:171], v168 offset:3072
	ds_read_b128 v[172:175], v184
	ds_read_b128 v[176:179], v184 offset:1024
	ds_read_b128 v[180:183], v184 offset:2048
	ds_read_b128 v[184:187], v184 offset:3072
	s_add_u32 s34, s34, 0x80000
	s_addc_u32 s35, s35, 0
	s_mov_b32 m0, s38
	ds_read_b128 v[188:191], v153 offset:32768
	ds_read_b128 v[192:195], v153 offset:33792
	ds_read_b128 v[200:203], v153 offset:34816
	ds_read_b128 v[204:207], v153 offset:35840
	ds_read_b128 v[208:211], v153 offset:36864
	ds_read_b128 v[212:215], v153 offset:37888
	ds_read_b128 v[216:219], v153 offset:38912
	ds_read_b128 v[220:223], v153 offset:39936
	global_load_lds_dwordx4 v128, s[34:35]
	s_mov_b32 m0, s39
	s_nop 0
	global_load_lds_dwordx4 v132, s[34:35]
	s_waitcnt vmcnt(8)
	s_waitcnt lgkmcnt(0)
	s_barrier
	s_setprio 1
	s_waitcnt lgkmcnt(0)
	v_mfma_f32_16x16x32_bf16 v[124:127], v[156:159], v[188:191], v[124:127]
	v_mfma_f32_16x16x32_bf16 v[120:123], v[164:167], v[188:191], v[120:123]
	v_mfma_f32_16x16x32_bf16 v[108:111], v[156:159], v[200:203], v[108:111]
	v_mfma_f32_16x16x32_bf16 v[104:107], v[164:167], v[200:203], v[104:107]
	v_mfma_f32_16x16x32_bf16 v[92:95], v[156:159], v[208:211], v[92:95]
	v_mfma_f32_16x16x32_bf16 v[88:91], v[164:167], v[208:211], v[88:91]
	v_mfma_f32_16x16x32_bf16 v[76:79], v[156:159], v[216:219], v[76:79]
	v_mfma_f32_16x16x32_bf16 v[72:75], v[164:167], v[216:219], v[72:75]
	v_mfma_f32_16x16x32_bf16 v[124:127], v[160:163], v[192:195], v[124:127]
	v_mfma_f32_16x16x32_bf16 v[120:123], v[168:171], v[192:195], v[120:123]
	v_mfma_f32_16x16x32_bf16 v[108:111], v[160:163], v[204:207], v[108:111]
	v_mfma_f32_16x16x32_bf16 v[104:107], v[168:171], v[204:207], v[104:107]
	v_mfma_f32_16x16x32_bf16 v[92:95], v[160:163], v[212:215], v[92:95]
	v_mfma_f32_16x16x32_bf16 v[88:91], v[168:171], v[212:215], v[88:91]
	v_mfma_f32_16x16x32_bf16 v[76:79], v[160:163], v[220:223], v[76:79]
	v_mfma_f32_16x16x32_bf16 v[72:75], v[168:171], v[220:223], v[72:75]
	s_setprio 0
	s_setprio 1
	v_mfma_f32_16x16x32_bf16 v[116:119], v[172:175], v[188:191], v[116:119]
	v_mfma_f32_16x16x32_bf16 v[112:115], v[180:183], v[188:191], v[112:115]
	v_mfma_f32_16x16x32_bf16 v[100:103], v[172:175], v[200:203], v[100:103]
	v_mfma_f32_16x16x32_bf16 v[96:99], v[180:183], v[200:203], v[96:99]
	v_mfma_f32_16x16x32_bf16 v[84:87], v[172:175], v[208:211], v[84:87]
	v_mfma_f32_16x16x32_bf16 v[80:83], v[180:183], v[208:211], v[80:83]
	v_mfma_f32_16x16x32_bf16 v[68:71], v[172:175], v[216:219], v[68:71]
	v_mfma_f32_16x16x32_bf16 v[64:67], v[180:183], v[216:219], v[64:67]
	v_mfma_f32_16x16x32_bf16 v[116:119], v[176:179], v[192:195], v[116:119]
	v_mfma_f32_16x16x32_bf16 v[112:115], v[184:187], v[192:195], v[112:115]
	v_mfma_f32_16x16x32_bf16 v[100:103], v[176:179], v[204:207], v[100:103]
	v_mfma_f32_16x16x32_bf16 v[96:99], v[184:187], v[204:207], v[96:99]
	v_mfma_f32_16x16x32_bf16 v[84:87], v[176:179], v[212:215], v[84:87]
	v_mfma_f32_16x16x32_bf16 v[80:83], v[184:187], v[212:215], v[80:83]
	v_mfma_f32_16x16x32_bf16 v[68:71], v[176:179], v[220:223], v[68:71]
	v_mfma_f32_16x16x32_bf16 v[64:67], v[184:187], v[220:223], v[64:67]
	s_setprio 0
	s_barrier
	s_add_i32 s34, s59, s33
	s_mov_b32 m0, s34
	ds_read_b128 v[188:191], v153 offset:49152
	ds_read_b128 v[192:195], v153 offset:50176
	ds_read_b128 v[200:203], v153 offset:51200
	ds_read_b128 v[204:207], v153 offset:52224
	ds_read_b128 v[208:211], v153 offset:53248
	ds_read_b128 v[212:215], v153 offset:54272
	ds_read_b128 v[216:219], v153 offset:55296
	ds_read_b128 v[220:223], v153 offset:56320
	global_load_lds_dwordx4 v130, s[98:99]
	s_add_i32 m0, s34, 0x2000
	s_add_u32 s2, s2, 0x80080
	s_addc_u32 s3, s3, 0
	s_add_i32 s34, s68, s33
	global_load_lds_dwordx4 v134, s[98:99]
	s_mov_b32 m0, s34
	s_nop 0
	global_load_lds_dwordx4 v130, s[2:3]
	s_add_i32 m0, s34, 0x2000
	s_nop 0
	global_load_lds_dwordx4 v134, s[2:3]
	s_mov_b32 m0, s42
	s_nop 0
	global_load_lds_dwordx4 v128, s[100:101]
	s_mov_b32 m0, s43
	s_nop 0
	global_load_lds_dwordx4 v132, s[100:101]
	s_waitcnt vmcnt(8)
	s_waitcnt lgkmcnt(0)
	s_barrier
	s_setprio 1
	s_waitcnt lgkmcnt(0)
	v_mfma_f32_16x16x32_bf16 v[60:63], v[156:159], v[188:191], v[60:63]
	v_mfma_f32_16x16x32_bf16 v[56:59], v[164:167], v[188:191], v[56:59]
	v_mfma_f32_16x16x32_bf16 v[44:47], v[156:159], v[200:203], v[44:47]
	v_mfma_f32_16x16x32_bf16 v[40:43], v[164:167], v[200:203], v[40:43]
	v_mfma_f32_16x16x32_bf16 v[28:31], v[156:159], v[208:211], v[28:31]
	v_mfma_f32_16x16x32_bf16 v[24:27], v[164:167], v[208:211], v[24:27]
	v_mfma_f32_16x16x32_bf16 v[12:15], v[156:159], v[216:219], v[12:15]
	v_mfma_f32_16x16x32_bf16 v[8:11], v[164:167], v[216:219], v[8:11]
	v_mfma_f32_16x16x32_bf16 v[60:63], v[160:163], v[192:195], v[60:63]
	v_mfma_f32_16x16x32_bf16 v[56:59], v[168:171], v[192:195], v[56:59]
	v_mfma_f32_16x16x32_bf16 v[44:47], v[160:163], v[204:207], v[44:47]
	v_mfma_f32_16x16x32_bf16 v[40:43], v[168:171], v[204:207], v[40:43]
	v_mfma_f32_16x16x32_bf16 v[28:31], v[160:163], v[212:215], v[28:31]
	v_mfma_f32_16x16x32_bf16 v[24:27], v[168:171], v[212:215], v[24:27]
	v_mfma_f32_16x16x32_bf16 v[12:15], v[160:163], v[220:223], v[12:15]
	v_mfma_f32_16x16x32_bf16 v[8:11], v[168:171], v[220:223], v[8:11]
	s_setprio 0
	s_setprio 1
	v_mfma_f32_16x16x32_bf16 v[52:55], v[172:175], v[188:191], v[52:55]
	v_mfma_f32_16x16x32_bf16 v[48:51], v[180:183], v[188:191], v[48:51]
	v_mfma_f32_16x16x32_bf16 v[36:39], v[172:175], v[200:203], v[36:39]
	v_mfma_f32_16x16x32_bf16 v[32:35], v[180:183], v[200:203], v[32:35]
	v_mfma_f32_16x16x32_bf16 v[20:23], v[172:175], v[208:211], v[20:23]
	v_mfma_f32_16x16x32_bf16 v[16:19], v[180:183], v[208:211], v[16:19]
	v_mfma_f32_16x16x32_bf16 v[4:7], v[172:175], v[216:219], v[4:7]
	v_mfma_f32_16x16x32_bf16 v[0:3], v[180:183], v[216:219], v[0:3]
	v_mfma_f32_16x16x32_bf16 v[52:55], v[176:179], v[192:195], v[52:55]
	v_mfma_f32_16x16x32_bf16 v[48:51], v[184:187], v[192:195], v[48:51]
	v_mfma_f32_16x16x32_bf16 v[36:39], v[176:179], v[204:207], v[36:39]
	v_mfma_f32_16x16x32_bf16 v[32:35], v[184:187], v[204:207], v[32:35]
	v_mfma_f32_16x16x32_bf16 v[20:23], v[176:179], v[212:215], v[20:23]
	v_mfma_f32_16x16x32_bf16 v[16:19], v[184:187], v[212:215], v[16:19]
	v_mfma_f32_16x16x32_bf16 v[4:7], v[176:179], v[220:223], v[4:7]
	v_mfma_f32_16x16x32_bf16 v[0:3], v[184:187], v[220:223], v[0:3]
	s_setprio 0
	s_barrier
	s_add_i32 s58, s58, 2
	s_add_u32 s30, s30, 0x100
	s_addc_u32 s31, s31, 0
	s_add_u32 s56, s56, 0x100
	s_addc_u32 s57, s57, 0
	s_cmp_gt_u32 s58, 29
	s_cbranch_scc0 .LBB0_629
	s_and_b64 vcc, exec, s[10:11]
	s_cbranch_vccz .LBB0_632
	s_barrier

; #define PG8_STAGE(bufoff, gbase, voff) do { _Pragma("unroll") for (int _i = 0; _i < 2; ++_i) \
;         __builtin_amdgcn_global_load_lds((const unsigned*)((const char*)(gbase) + (voff)[_i]), (PG8_LAS unsigned*)(lds + (bufoff) + ldsw + _i * 8192), 16, 0, 0); } while (0)
; #define PG8_LDA(dst, b, h) do { _Pragma("unroll") for (int m = 0; m < 4; ++m) _Pragma("unroll") for (int k = 0; k < 2; ++k) dst[m][k] = *(const PG8_LAS bf16x8*)(lds + PG8_SA(b, h) + aoff + m * 2048 + k * 1024); } while (0)
; #define PG8_LDB(dst, b, h) do { _Pragma("unroll") for (int n = 0; n < 2; ++n) _Pragma("unroll") for (int k = 0; k < 2; ++k) dst[n][k] = *(const PG8_LAS bf16x8*)(lds + PG8_SB(b, h) + boff + n * 2048 + k * 1024); } while (0)
; #define PG8_MMA(ai, bj, At, Bt) do { __builtin_amdgcn_s_setprio(1); _Pragma("unroll") for (int m = 0; m < 4; ++m) _Pragma("unroll") for (int n = 0; n < 2; ++n) _Pragma("unroll") for (int k = 0; k < 2; ++k) \
;         acc[ai][bj][m][n] = __builtin_amdgcn_mfma_f32_16x16x32_bf16(Bt[n][k], At[m][k], acc[ai][bj][m][n], 0, 0, 0); __builtin_amdgcn_s_setprio(0); } while (0)
; #define PG8_WAIT_V(n) asm volatile("s_waitcnt vmcnt(" #n ")" ::: "memory")
; #define PG8_WAIT_L(n) asm volatile("s_waitcnt lgkmcnt(" #n ")" ::: "memory")
; #define PG8_BAR __builtin_amdgcn_s_barrier()
; template <class Epi, class Sched, bool ALIGN_EPI = false, bool SP2 = false>
; __device__ __forceinline__ void gemm_phase(PG8_LAS unsigned char* lds, const Gemm g, const Sched& S, const Epi& E) {
;     ...
;             const char* a1 = cA + (size_t)(t + 1) * kstep;
;             const char* a2 = last ? nA : cA + (size_t)(t + 2) * kstep; const char* b2 = last ? nB : cB + (size_t)(t + 2) * kstep;
;             const char* a3 = a2 + kstep; const char* b3 = b2 + kstep;
;             if (last && has_next) S.a_ready(nxt);
;             if constexpr (SP2) {
;             PG8_LDB(B0, 0, 0); PG8_LDB(B1, 0, 1); PG8_SCHED; PG8_LDA(At, 0, 0); PG8_STAGE(PG8_SA(1, 1), a1 + hstep, voffA);
;             PG8_WAIT_V(8); PG8_WAIT_L(0); PG8_BAR; PG8_MMA(0, 0, At, B0); PG8_MMA(0, 1, At, B1); PG8_BAR; PG8_SCHED;
;             PG8_LDA(At, 0, 1); PG8_STAGE(PG8_SB(0, 0), b2, voffB); PG8_STAGE(PG8_SB(0, 1), b2 + hstep, voffB); PG8_STAGE(PG8_SA(0, 0), a2, voffA);
;             PG8_WAIT_V(8); PG8_WAIT_L(0); PG8_BAR; PG8_MMA(1, 0, At, B0); PG8_MMA(1, 1, At, B1); PG8_BAR; PG8_SCHED;
.LBB0_717:
	ds_read_b128 v[150:153], v158
	ds_read_b128 v[162:165], v158 offset:1024
	ds_read_b128 v[166:169], v158 offset:2048
	ds_read_b128 v[170:173], v158 offset:3072
	ds_read_b128 v[174:177], v159
	ds_read_b128 v[178:181], v159 offset:1024
	ds_read_b128 v[182:185], v159 offset:2048
	ds_read_b128 v[186:189], v159 offset:3072
	s_add_u32 s2, s28, 0xffe00080
	s_addc_u32 s3, s29, -1
	s_cmpk_eq_i32 s50, 0x7c
	s_cselect_b32 s31, s21, s3
	s_cselect_b32 s30, s46, s2
	s_cselect_b32 s3, s19, s49
	s_cselect_b32 s2, s47, s48
	s_add_i32 m0, s27, 0xc000
	ds_read_b128 v[190:193], v160
	ds_read_b128 v[194:197], v160 offset:1024
	ds_read_b128 v[198:201], v160 offset:2048
	ds_read_b128 v[202:205], v160 offset:3072
	ds_read_b128 v[206:209], v160 offset:4096
	ds_read_b128 v[210:213], v160 offset:5120
	ds_read_b128 v[214:217], v160 offset:6144
	ds_read_b128 v[218:221], v160 offset:7168
	global_load_lds_dwordx4 v142, s[28:29]
	s_add_i32 m0, s27, 0xe000
	s_nop 0
	global_load_lds_dwordx4 v144, s[28:29]
	s_waitcnt vmcnt(8)
	s_waitcnt lgkmcnt(0)
	s_barrier
	s_setprio 1
	s_waitcnt lgkmcnt(0)
	v_mfma_f32_16x16x32_bf16 v[124:127], v[150:153], v[190:193], v[124:127]
	v_mfma_f32_16x16x32_bf16 v[120:123], v[166:169], v[190:193], v[120:123]
	v_mfma_f32_16x16x32_bf16 v[108:111], v[150:153], v[198:201], v[108:111]
	v_mfma_f32_16x16x32_bf16 v[104:107], v[166:169], v[198:201], v[104:107]
	v_mfma_f32_16x16x32_bf16 v[92:95], v[150:153], v[206:209], v[92:95]
	v_mfma_f32_16x16x32_bf16 v[88:91], v[166:169], v[206:209], v[88:91]
	v_mfma_f32_16x16x32_bf16 v[76:79], v[150:153], v[214:217], v[76:79]
	v_mfma_f32_16x16x32_bf16 v[72:75], v[166:169], v[214:217], v[72:75]
	v_mfma_f32_16x16x32_bf16 v[124:127], v[162:165], v[194:197], v[124:127]
	v_mfma_f32_16x16x32_bf16 v[120:123], v[170:173], v[194:197], v[120:123]
	v_mfma_f32_16x16x32_bf16 v[108:111], v[162:165], v[202:205], v[108:111]
	v_mfma_f32_16x16x32_bf16 v[104:107], v[170:173], v[202:205], v[104:107]
	v_mfma_f32_16x16x32_bf16 v[92:95], v[162:165], v[210:213], v[92:95]
	v_mfma_f32_16x16x32_bf16 v[88:91], v[170:173], v[210:213], v[88:91]
	v_mfma_f32_16x16x32_bf16 v[76:79], v[162:165], v[218:221], v[76:79]
	v_mfma_f32_16x16x32_bf16 v[72:75], v[170:173], v[218:221], v[72:75]
	s_setprio 0
	s_setprio 1
	v_mfma_f32_16x16x32_bf16 v[116:119], v[174:177], v[190:193], v[116:119]
	v_mfma_f32_16x16x32_bf16 v[112:115], v[182:185], v[190:193], v[112:115]
	v_mfma_f32_16x16x32_bf16 v[100:103], v[174:177], v[198:201], v[100:103]
	v_mfma_f32_16x16x32_bf16 v[96:99], v[182:185], v[198:201], v[96:99]
	v_mfma_f32_16x16x32_bf16 v[84:87], v[174:177], v[206:209], v[84:87]
	v_mfma_f32_16x16x32_bf16 v[80:83], v[182:185], v[206:209], v[80:83]
	v_mfma_f32_16x16x32_bf16 v[68:71], v[174:177], v[214:217], v[68:71]
	v_mfma_f32_16x16x32_bf16 v[64:67], v[182:185], v[214:217], v[64:67]
	v_mfma_f32_16x16x32_bf16 v[116:119], v[178:181], v[194:197], v[116:119]
	v_mfma_f32_16x16x32_bf16 v[112:115], v[186:189], v[194:197], v[112:115]
	v_mfma_f32_16x16x32_bf16 v[100:103], v[178:181], v[202:205], v[100:103]
	v_mfma_f32_16x16x32_bf16 v[96:99], v[186:189], v[202:205], v[96:99]
	v_mfma_f32_16x16x32_bf16 v[84:87], v[178:181], v[210:213], v[84:87]
	v_mfma_f32_16x16x32_bf16 v[80:83], v[186:189], v[210:213], v[80:83]
	v_mfma_f32_16x16x32_bf16 v[68:71], v[178:181], v[218:221], v[68:71]
	v_mfma_f32_16x16x32_bf16 v[64:67], v[186:189], v[218:221], v[64:67]
	s_setprio 0
	s_barrier
	s_add_u32 s98, s2, s14
	s_addc_u32 s99, s3, s15
	s_add_u32 s100, s30, s14
	s_addc_u32 s101, s31, s15
	s_add_i32 s51, s43, s34
	s_mov_b32 m0, s51
	ds_read_b128 v[190:193], v160 offset:16384
	ds_read_b128 v[194:197], v160 offset:17408
	ds_read_b128 v[198:201], v160 offset:18432
	ds_read_b128 v[202:205], v160 offset:19456
	ds_read_b128 v[206:209], v160 offset:20480
	ds_read_b128 v[210:213], v160 offset:21504
	ds_read_b128 v[214:217], v160 offset:22528
	ds_read_b128 v[218:221], v160 offset:23552
	global_load_lds_dwordx4 v134, s[2:3]
	s_add_i32 m0, s51, 0x2000
	s_add_u32 s52, s2, 0x200000
	s_addc_u32 s53, s3, 0
	s_add_i32 s51, s44, s34
	global_load_lds_dwordx4 v138, s[2:3]
	s_mov_b32 m0, s51
	s_nop 0
	global_load_lds_dwordx4 v134, s[52:53]
	s_add_i32 m0, s51, 0x2000
	s_nop 0
	global_load_lds_dwordx4 v138, s[52:53]
	s_mov_b32 m0, s27
	s_nop 0
	global_load_lds_dwordx4 v132, s[30:31]
	s_mov_b32 m0, s35
	s_nop 0
	global_load_lds_dwordx4 v136, s[30:31]
	s_waitcnt vmcnt(8)
	s_waitcnt lgkmcnt(0)
	s_barrier
	s_setprio 1
	s_waitcnt lgkmcnt(0)
	v_mfma_f32_16x16x32_bf16 v[60:63], v[150:153], v[190:193], v[60:63]
	v_mfma_f32_16x16x32_bf16 v[56:59], v[166:169], v[190:193], v[56:59]
	v_mfma_f32_16x16x32_bf16 v[44:47], v[150:153], v[198:201], v[44:47]
	v_mfma_f32_16x16x32_bf16 v[40:43], v[166:169], v[198:201], v[40:43]
	v_mfma_f32_16x16x32_bf16 v[28:31], v[150:153], v[206:209], v[28:31]
	v_mfma_f32_16x16x32_bf16 v[24:27], v[166:169], v[206:209], v[24:27]
	v_mfma_f32_16x16x32_bf16 v[12:15], v[150:153], v[214:217], v[12:15]
	v_mfma_f32_16x16x32_bf16 v[8:11], v[166:169], v[214:217], v[8:11]
	v_mfma_f32_16x16x32_bf16 v[60:63], v[162:165], v[194:197], v[60:63]
	v_mfma_f32_16x16x32_bf16 v[56:59], v[170:173], v[194:197], v[56:59]
	v_mfma_f32_16x16x32_bf16 v[44:47], v[162:165], v[202:205], v[44:47]
	v_mfma_f32_16x16x32_bf16 v[40:43], v[170:173], v[202:205], v[40:43]
	v_mfma_f32_16x16x32_bf16 v[28:31], v[162:165], v[210:213], v[28:31]
	v_mfma_f32_16x16x32_bf16 v[24:27], v[170:173], v[210:213], v[24:27]
	v_mfma_f32_16x16x32_bf16 v[12:15], v[162:165], v[218:221], v[12:15]
	v_mfma_f32_16x16x32_bf16 v[8:11], v[170:173], v[218:221], v[8:11]
	s_setprio 0
	s_setprio 1
	v_mfma_f32_16x16x32_bf16 v[52:55], v[174:177], v[190:193], v[52:55]
	v_mfma_f32_16x16x32_bf16 v[48:51], v[182:185], v[190:193], v[48:51]
	v_mfma_f32_16x16x32_bf16 v[36:39], v[174:177], v[198:201], v[36:39]
	v_mfma_f32_16x16x32_bf16 v[32:35], v[182:185], v[198:201], v[32:35]
	v_mfma_f32_16x16x32_bf16 v[20:23], v[174:177], v[206:209], v[20:23]
	v_mfma_f32_16x16x32_bf16 v[16:19], v[182:185], v[206:209], v[16:19]
	v_mfma_f32_16x16x32_bf16 v[4:7], v[174:177], v[214:217], v[4:7]
	v_mfma_f32_16x16x32_bf16 v[0:3], v[182:185], v[214:217], v[0:3]
	v_mfma_f32_16x16x32_bf16 v[52:55], v[178:181], v[194:197], v[52:55]
	v_mfma_f32_16x16x32_bf16 v[48:51], v[186:189], v[194:197], v[48:51]
	v_mfma_f32_16x16x32_bf16 v[36:39], v[178:181], v[202:205], v[36:39]
	v_mfma_f32_16x16x32_bf16 v[32:35], v[186:189], v[202:205], v[32:35]
	v_mfma_f32_16x16x32_bf16 v[20:23], v[178:181], v[210:213], v[20:23]
	v_mfma_f32_16x16x32_bf16 v[16:19], v[186:189], v[210:213], v[16:19]
	v_mfma_f32_16x16x32_bf16 v[4:7], v[178:181], v[218:221], v[4:7]
	v_mfma_f32_16x16x32_bf16 v[0:3], v[186:189], v[218:221], v[0:3]
	s_setprio 0
	s_barrier
; #define PG8_STAGE(bufoff, gbase, voff) do { _Pragma("unroll") for (int _i = 0; _i < 2; ++_i) \
;         __builtin_amdgcn_global_load_lds((const unsigned*)((const char*)(gbase) + (voff)[_i]), (PG8_LAS unsigned*)(lds + (bufoff) + ldsw + _i * 8192), 16, 0, 0); } while (0)
; #define PG8_LDA(dst, b, h) do { _Pragma("unroll") for (int m = 0; m < 4; ++m) _Pragma("unroll") for (int k = 0; k < 2; ++k) dst[m][k] = *(const PG8_LAS bf16x8*)(lds + PG8_SA(b, h) + aoff + m * 2048 + k * 1024); } while (0)
; #define PG8_LDB(dst, b, h) do { _Pragma("unroll") for (int n = 0; n < 2; ++n) _Pragma("unroll") for (int k = 0; k < 2; ++k) dst[n][k] = *(const PG8_LAS bf16x8*)(lds + PG8_SB(b, h) + boff + n * 2048 + k * 1024); } while (0)
; #define PG8_MMA(ai, bj, At, Bt) do { __builtin_amdgcn_s_setprio(1); _Pragma("unroll") for (int m = 0; m < 4; ++m) _Pragma("unroll") for (int n = 0; n < 2; ++n) _Pragma("unroll") for (int k = 0; k < 2; ++k) \
;         acc[ai][bj][m][n] = __builtin_amdgcn_mfma_f32_16x16x32_bf16(Bt[n][k], At[m][k], acc[ai][bj][m][n], 0, 0, 0); __builtin_amdgcn_s_setprio(0); } while (0)
; #define PG8_WAIT_V(n) asm volatile("s_waitcnt vmcnt(" #n ")" ::: "memory")
; #define PG8_WAIT_L(n) asm volatile("s_waitcnt lgkmcnt(" #n ")" ::: "memory")
; #define PG8_BAR __builtin_amdgcn_s_barrier()
; #define PG8_SCHED __builtin_amdgcn_sched_barrier(0)
; template <class Epi, class Sched, bool ALIGN_EPI = false, bool SP2 = false>
; __device__ __forceinline__ void gemm_phase(PG8_LAS unsigned char* lds, const Gemm g, const Sched& S, const Epi& E) {
;     ...
;             PG8_LDB(B0, 1, 0); PG8_LDB(B1, 1, 1); PG8_SCHED; PG8_LDA(At, 1, 0); PG8_STAGE(PG8_SA(0, 1), a2 + hstep, voffA);
;             PG8_WAIT_V(8); PG8_WAIT_L(0); PG8_BAR; PG8_MMA(0, 0, At, B0); PG8_MMA(0, 1, At, B1); PG8_BAR; PG8_SCHED;
;             PG8_LDA(At, 1, 1); PG8_STAGE(PG8_SB(1, 0), b3, voffB); PG8_STAGE(PG8_SB(1, 1), b3 + hstep, voffB); PG8_STAGE(PG8_SA(1, 0), a3, voffA);
;             PG8_WAIT_V(8); PG8_WAIT_L(0); PG8_BAR; PG8_MMA(1, 0, At, B0); PG8_MMA(1, 1, At, B1); PG8_BAR; PG8_SCHED;
;     ...
;         if constexpr (ALIGN_EPI) { if (wr == 0) PG8_BAR; }
;         if constexpr (!Epi::AFTER_DRAIN) { E(acc, cur, wr, wc, fr, fq); S.done(cur); }
;         if (!has_next) break;
	s_add_i32 s51, 0, 0x18000
	v_add_u32_e32 v155, s51, v157
	s_add_i32 s52, 0, 0x1c000
	ds_read_b128 v[150:153], v155
	ds_read_b128 v[162:165], v155 offset:1024
	ds_read_b128 v[166:169], v155 offset:2048
	ds_read_b128 v[170:173], v155 offset:3072
	v_add_u32_e32 v155, s52, v157
	ds_read_b128 v[174:177], v155
	ds_read_b128 v[178:181], v155 offset:1024
	ds_read_b128 v[182:185], v155 offset:2048
	ds_read_b128 v[186:189], v155 offset:3072
	s_add_u32 s30, s30, 0x200000
	s_addc_u32 s31, s31, 0
	s_mov_b32 m0, s36
	ds_read_b128 v[190:193], v160 offset:32768
	ds_read_b128 v[194:197], v160 offset:33792
	ds_read_b128 v[198:201], v160 offset:34816
	ds_read_b128 v[202:205], v160 offset:35840
	ds_read_b128 v[206:209], v160 offset:36864
	ds_read_b128 v[210:213], v160 offset:37888
	ds_read_b128 v[214:217], v160 offset:38912
	ds_read_b128 v[218:221], v160 offset:39936
	global_load_lds_dwordx4 v132, s[30:31]
	s_mov_b32 m0, s37
	s_nop 0
	global_load_lds_dwordx4 v136, s[30:31]
	s_waitcnt vmcnt(8)
	s_waitcnt lgkmcnt(0)
	s_barrier
	s_setprio 1
	s_waitcnt lgkmcnt(0)
	v_mfma_f32_16x16x32_bf16 v[124:127], v[150:153], v[190:193], v[124:127]
	v_mfma_f32_16x16x32_bf16 v[120:123], v[166:169], v[190:193], v[120:123]
	v_mfma_f32_16x16x32_bf16 v[108:111], v[150:153], v[198:201], v[108:111]
	v_mfma_f32_16x16x32_bf16 v[104:107], v[166:169], v[198:201], v[104:107]
	v_mfma_f32_16x16x32_bf16 v[92:95], v[150:153], v[206:209], v[92:95]
	v_mfma_f32_16x16x32_bf16 v[88:91], v[166:169], v[206:209], v[88:91]
	v_mfma_f32_16x16x32_bf16 v[76:79], v[150:153], v[214:217], v[76:79]
	v_mfma_f32_16x16x32_bf16 v[72:75], v[166:169], v[214:217], v[72:75]
	v_mfma_f32_16x16x32_bf16 v[124:127], v[162:165], v[194:197], v[124:127]
	v_mfma_f32_16x16x32_bf16 v[120:123], v[170:173], v[194:197], v[120:123]
	v_mfma_f32_16x16x32_bf16 v[108:111], v[162:165], v[202:205], v[108:111]
	v_mfma_f32_16x16x32_bf16 v[104:107], v[170:173], v[202:205], v[104:107]
	v_mfma_f32_16x16x32_bf16 v[92:95], v[162:165], v[210:213], v[92:95]
	v_mfma_f32_16x16x32_bf16 v[88:91], v[170:173], v[210:213], v[88:91]
	v_mfma_f32_16x16x32_bf16 v[76:79], v[162:165], v[218:221], v[76:79]
	v_mfma_f32_16x16x32_bf16 v[72:75], v[170:173], v[218:221], v[72:75]
	s_setprio 0
	s_setprio 1
	v_mfma_f32_16x16x32_bf16 v[116:119], v[174:177], v[190:193], v[116:119]
	v_mfma_f32_16x16x32_bf16 v[112:115], v[182:185], v[190:193], v[112:115]
	v_mfma_f32_16x16x32_bf16 v[100:103], v[174:177], v[198:201], v[100:103]
	v_mfma_f32_16x16x32_bf16 v[96:99], v[182:185], v[198:201], v[96:99]
	v_mfma_f32_16x16x32_bf16 v[84:87], v[174:177], v[206:209], v[84:87]
	v_mfma_f32_16x16x32_bf16 v[80:83], v[182:185], v[206:209], v[80:83]
	v_mfma_f32_16x16x32_bf16 v[68:71], v[174:177], v[214:217], v[68:71]
	v_mfma_f32_16x16x32_bf16 v[64:67], v[182:185], v[214:217], v[64:67]
	v_mfma_f32_16x16x32_bf16 v[116:119], v[178:181], v[194:197], v[116:119]
	v_mfma_f32_16x16x32_bf16 v[112:115], v[186:189], v[194:197], v[112:115]
	v_mfma_f32_16x16x32_bf16 v[100:103], v[178:181], v[202:205], v[100:103]
	v_mfma_f32_16x16x32_bf16 v[96:99], v[186:189], v[202:205], v[96:99]
	v_mfma_f32_16x16x32_bf16 v[84:87], v[178:181], v[210:213], v[84:87]
	v_mfma_f32_16x16x32_bf16 v[80:83], v[186:189], v[210:213], v[80:83]
	v_mfma_f32_16x16x32_bf16 v[68:71], v[178:181], v[218:221], v[68:71]
	v_mfma_f32_16x16x32_bf16 v[64:67], v[186:189], v[218:221], v[64:67]
	s_setprio 0
	s_barrier
	s_add_i32 s30, s51, s34
	s_mov_b32 m0, s30
	ds_read_b128 v[190:193], v160 offset:49152
	ds_read_b128 v[194:197], v160 offset:50176
	ds_read_b128 v[198:201], v160 offset:51200
	ds_read_b128 v[202:205], v160 offset:52224
	ds_read_b128 v[206:209], v160 offset:53248
	ds_read_b128 v[210:213], v160 offset:54272
	ds_read_b128 v[214:217], v160 offset:55296
	ds_read_b128 v[218:221], v160 offset:56320
	global_load_lds_dwordx4 v134, s[98:99]
	s_add_i32 m0, s30, 0x2000
	s_add_u32 s2, s2, 0x200080
	s_addc_u32 s3, s3, 0
	s_add_i32 s30, s52, s34
	global_load_lds_dwordx4 v138, s[98:99]
	s_mov_b32 m0, s30
	s_nop 0
	global_load_lds_dwordx4 v134, s[2:3]
	s_add_i32 m0, s30, 0x2000
	s_nop 0
	global_load_lds_dwordx4 v138, s[2:3]
	s_mov_b32 m0, s39
	s_nop 0
	global_load_lds_dwordx4 v132, s[100:101]
	s_mov_b32 m0, s40
	s_nop 0
	global_load_lds_dwordx4 v136, s[100:101]
	s_waitcnt vmcnt(8)
	s_waitcnt lgkmcnt(0)
	s_barrier
	s_setprio 1
	s_waitcnt lgkmcnt(0)
	v_mfma_f32_16x16x32_bf16 v[60:63], v[150:153], v[190:193], v[60:63]
	v_mfma_f32_16x16x32_bf16 v[56:59], v[166:169], v[190:193], v[56:59]
	v_mfma_f32_16x16x32_bf16 v[44:47], v[150:153], v[198:201], v[44:47]
	v_mfma_f32_16x16x32_bf16 v[40:43], v[166:169], v[198:201], v[40:43]
	v_mfma_f32_16x16x32_bf16 v[28:31], v[150:153], v[206:209], v[28:31]
	v_mfma_f32_16x16x32_bf16 v[24:27], v[166:169], v[206:209], v[24:27]
	v_mfma_f32_16x16x32_bf16 v[12:15], v[150:153], v[214:217], v[12:15]
	v_mfma_f32_16x16x32_bf16 v[8:11], v[166:169], v[214:217], v[8:11]
	v_mfma_f32_16x16x32_bf16 v[60:63], v[162:165], v[194:197], v[60:63]
	v_mfma_f32_16x16x32_bf16 v[56:59], v[170:173], v[194:197], v[56:59]
	v_mfma_f32_16x16x32_bf16 v[44:47], v[162:165], v[202:205], v[44:47]
	v_mfma_f32_16x16x32_bf16 v[40:43], v[170:173], v[202:205], v[40:43]
	v_mfma_f32_16x16x32_bf16 v[28:31], v[162:165], v[210:213], v[28:31]
	v_mfma_f32_16x16x32_bf16 v[24:27], v[170:173], v[210:213], v[24:27]
	v_mfma_f32_16x16x32_bf16 v[12:15], v[162:165], v[218:221], v[12:15]
	v_mfma_f32_16x16x32_bf16 v[8:11], v[170:173], v[218:221], v[8:11]
	s_setprio 0
	s_setprio 1
	v_mfma_f32_16x16x32_bf16 v[52:55], v[174:177], v[190:193], v[52:55]
	v_mfma_f32_16x16x32_bf16 v[48:51], v[182:185], v[190:193], v[48:51]
	v_mfma_f32_16x16x32_bf16 v[36:39], v[174:177], v[198:201], v[36:39]
	v_mfma_f32_16x16x32_bf16 v[32:35], v[182:185], v[198:201], v[32:35]
	v_mfma_f32_16x16x32_bf16 v[20:23], v[174:177], v[206:209], v[20:23]
	v_mfma_f32_16x16x32_bf16 v[16:19], v[182:185], v[206:209], v[16:19]
	v_mfma_f32_16x16x32_bf16 v[4:7], v[174:177], v[214:217], v[4:7]
	v_mfma_f32_16x16x32_bf16 v[0:3], v[182:185], v[214:217], v[0:3]
	v_mfma_f32_16x16x32_bf16 v[52:55], v[178:181], v[194:197], v[52:55]
	v_mfma_f32_16x16x32_bf16 v[48:51], v[186:189], v[194:197], v[48:51]
	v_mfma_f32_16x16x32_bf16 v[36:39], v[178:181], v[202:205], v[36:39]
	v_mfma_f32_16x16x32_bf16 v[32:35], v[186:189], v[202:205], v[32:35]
	v_mfma_f32_16x16x32_bf16 v[20:23], v[178:181], v[210:213], v[20:23]
	v_mfma_f32_16x16x32_bf16 v[16:19], v[186:189], v[210:213], v[16:19]
	v_mfma_f32_16x16x32_bf16 v[4:7], v[178:181], v[218:221], v[4:7]
	v_mfma_f32_16x16x32_bf16 v[0:3], v[186:189], v[218:221], v[0:3]
	s_setprio 0
	s_barrier
	s_add_i32 s50, s50, 2
	s_add_u32 s28, s28, 0x100
	s_addc_u32 s29, s29, 0
	s_add_u32 s48, s48, 0x100
	s_addc_u32 s49, s49, 0
	s_cmpk_gt_u32 s50, 0x7d
	s_cbranch_scc0 .LBB0_717
	s_and_b64 vcc, exec, s[16:17]
	s_cbranch_vccz .LBB0_720
	s_barrier

; __global__ void __launch_bounds__(512, 2) fwd_kernel(Args a) {
	.amdhsa_kernel _Z10fwd_kernel4Args
		.amdhsa_group_segment_fixed_size 0
		.amdhsa_private_segment_fixed_size 0
		.amdhsa_kernarg_size 400
		.amdhsa_user_sgpr_count 2
		.amdhsa_user_sgpr_dispatch_ptr 0
		.amdhsa_user_sgpr_queue_ptr 0
		.amdhsa_user_sgpr_kernarg_segment_ptr 1
		.amdhsa_user_sgpr_dispatch_id 0
		.amdhsa_user_sgpr_kernarg_preload_length 0
		.amdhsa_user_sgpr_kernarg_preload_offset 0
		.amdhsa_user_sgpr_private_segment_size 0
		.amdhsa_uses_dynamic_stack 0
		.amdhsa_enable_private_segment 0
		.amdhsa_system_sgpr_workgroup_id_x 1
		.amdhsa_system_sgpr_workgroup_id_y 0
		.amdhsa_system_sgpr_workgroup_id_z 0
		.amdhsa_system_sgpr_workgroup_info 0
		.amdhsa_system_vgpr_workitem_id 2
		.amdhsa_next_free_vgpr 256
		.amdhsa_next_free_sgpr 102
		.amdhsa_accum_offset 256
		.amdhsa_reserve_vcc 1
		.amdhsa_float_round_mode_32 0
		.amdhsa_float_round_mode_16_64 0
		.amdhsa_float_denorm_mode_32 3
		.amdhsa_float_denorm_mode_16_64 3
		.amdhsa_dx10_clamp 1
		.amdhsa_ieee_mode 1
		.amdhsa_fp16_overflow 0
		.amdhsa_tg_split 0
		.amdhsa_exception_fp_ieee_invalid_op 0
		.amdhsa_exception_fp_denorm_src 0
		.amdhsa_exception_fp_ieee_div_zero 0
		.amdhsa_exception_fp_ieee_overflow 0
		.amdhsa_exception_fp_ieee_underflow 0
		.amdhsa_exception_fp_ieee_inexact 0
		.amdhsa_exception_int_div_zero 0
	.end_amdhsa_kernel

; __global__ void __launch_bounds__(512, 2) fwd_kernel(Args a) {
.Lfunc_end0:
	.size	_Z10fwd_kernel4Args, .Lfunc_end0-_Z10fwd_kernel4Args
	.set _Z10fwd_kernel4Args.num_vgpr, 256
	.set _Z10fwd_kernel4Args.num_agpr, 0
	.set _Z10fwd_kernel4Args.numbered_sgpr, 102
	.set _Z10fwd_kernel4Args.num_named_barrier, 0
	.set _Z10fwd_kernel4Args.private_seg_size, 0
	.set _Z10fwd_kernel4Args.uses_vcc, 1
	.set _Z10fwd_kernel4Args.uses_flat_scratch, 0
	.set _Z10fwd_kernel4Args.has_dyn_sized_stack, 0
	.set _Z10fwd_kernel4Args.has_recursion, 0
	.set _Z10fwd_kernel4Args.has_indirect_call, 0

; __global__ void __launch_bounds__(512, 2) fwd_kernel(Args a) {
amdhsa.kernels:
  - .agpr_count:     0
    .args:
      - .offset:         0
        .size:           144
        .value_kind:     by_value
      - .offset:         144
        .size:           4
        .value_kind:     hidden_block_count_x
      - .offset:         148
        .size:           4
        .value_kind:     hidden_block_count_y
      - .offset:         152
        .size:           4
        .value_kind:     hidden_block_count_z
      - .offset:         156
        .size:           2
        .value_kind:     hidden_group_size_x
      - .offset:         158
        .size:           2
        .value_kind:     hidden_group_size_y
      - .offset:         160
        .size:           2
        .value_kind:     hidden_group_size_z
      - .offset:         162
        .size:           2
        .value_kind:     hidden_remainder_x
      - .offset:         164
        .size:           2
        .value_kind:     hidden_remainder_y
      - .offset:         166
        .size:           2
        .value_kind:     hidden_remainder_z
      - .offset:         184
        .size:           8
        .value_kind:     hidden_global_offset_x
      - .offset:         192
        .size:           8
        .value_kind:     hidden_global_offset_y
      - .offset:         200
        .size:           8
        .value_kind:     hidden_global_offset_z
      - .offset:         208
        .size:           2
        .value_kind:     hidden_grid_dims
      - .offset:         232
        .size:           8
        .value_kind:     hidden_multigrid_sync_arg
      - .offset:         264
        .size:           4
        .value_kind:     hidden_dynamic_lds_size
    .group_segment_fixed_size: 0
    .kernarg_segment_align: 8
    .kernarg_segment_size: 400
    .language:       OpenCL C
    .language_version:
      - 2
      - 0
    .max_flat_workgroup_size: 512
    .name:           _Z10fwd_kernel4Args
    .private_segment_fixed_size: 0
    .sgpr_count:     108
    .sgpr_spill_count: 77
    .symbol:         _Z10fwd_kernel4Args.kd
    .uniform_work_group_size: 1
    .uses_dynamic_stack: false
    .vgpr_count:     256
    .vgpr_spill_count: 0
    .wavefront_size: 64
